# K-loop staging balance 3+5 DMA stages per K-tile (SA(b,0) i1 piece moved to the next 2-stage load segment, waits vmcnt 8/7) on top of early-MFMA N=4
# speedup vs baseline: 1.0021x; 1.0021x over previous
.LBB0_219:
	s_add_u32 s98, s34, 0xfffc0000
	s_addc_u32 s99, s35, -1
	s_mov_b32 m0, s52
	s_nop 0
	global_load_lds_dwordx4 v134, s[98:99]
	ds_read_b128 v[180:183], v173
	ds_read_b128 v[184:187], v173 offset:1024
	ds_read_b128 v[188:191], v173 offset:2048
	ds_read_b128 v[192:195], v173 offset:3072
	ds_read_b128 v[196:199], v174
	ds_read_b128 v[200:203], v174 offset:1024
	ds_read_b128 v[204:207], v174 offset:2048
	ds_read_b128 v[208:211], v174 offset:3072
	s_add_u32 s36, s34, 0xfffc0080
	s_addc_u32 s37, s35, -1
	s_cmp_eq_u32 s59, 12
	s_cselect_b32 s39, s1, s37
	s_cselect_b32 s38, s9, s36
	s_cselect_b32 s37, s12, s58
	s_cselect_b32 s36, s25, s27
	v_lshl_add_u64 v[156:157], s[34:35], 0, v[142:143]
	s_add_i32 m0, s45, 0xc000
	ds_read_b128 v[212:215], v175
	ds_read_b128 v[216:219], v175 offset:1024
	ds_read_b128 v[220:223], v175 offset:2048
	ds_read_b128 v[224:227], v175 offset:3072
	ds_read_b128 v[228:231], v175 offset:4096
	ds_read_b128 v[232:235], v175 offset:5120
	ds_read_b128 v[236:239], v175 offset:6144
	ds_read_b128 v[240:243], v175 offset:7168
	global_load_lds_dwordx4 v[156:157], off
	v_lshl_add_u64 v[156:157], s[34:35], 0, v[140:141]
	s_add_i32 m0, s45, 0xe000
	s_nop 0
	global_load_lds_dwordx4 v[156:157], off
	s_waitcnt vmcnt(8)
	s_waitcnt lgkmcnt(0)
	v_mfma_f32_16x16x32_bf16 v[126:129], v[180:183], v[212:215], v[126:129]
	v_mfma_f32_16x16x32_bf16 v[122:125], v[188:191], v[212:215], v[122:125]
	v_mfma_f32_16x16x32_bf16 v[110:113], v[180:183], v[220:223], v[110:113]
	v_mfma_f32_16x16x32_bf16 v[106:109], v[188:191], v[220:223], v[106:109]
	s_barrier
	s_setprio 1
	v_mfma_f32_16x16x32_bf16 v[94:97], v[180:183], v[228:231], v[94:97]
	v_mfma_f32_16x16x32_bf16 v[90:93], v[188:191], v[228:231], v[90:93]
	v_mfma_f32_16x16x32_bf16 v[78:81], v[180:183], v[236:239], v[78:81]
	v_mfma_f32_16x16x32_bf16 v[74:77], v[188:191], v[236:239], v[74:77]
	v_mfma_f32_16x16x32_bf16 v[126:129], v[184:187], v[216:219], v[126:129]
	v_mfma_f32_16x16x32_bf16 v[122:125], v[192:195], v[216:219], v[122:125]
	v_mfma_f32_16x16x32_bf16 v[110:113], v[184:187], v[224:227], v[110:113]
	v_mfma_f32_16x16x32_bf16 v[106:109], v[192:195], v[224:227], v[106:109]
	v_mfma_f32_16x16x32_bf16 v[94:97], v[184:187], v[232:235], v[94:97]
	v_mfma_f32_16x16x32_bf16 v[90:93], v[192:195], v[232:235], v[90:93]
	v_mfma_f32_16x16x32_bf16 v[78:81], v[184:187], v[240:243], v[78:81]
	v_mfma_f32_16x16x32_bf16 v[74:77], v[192:195], v[240:243], v[74:77]
	v_mfma_f32_16x16x32_bf16 v[118:121], v[196:199], v[212:215], v[118:121]
	v_mfma_f32_16x16x32_bf16 v[114:117], v[204:207], v[212:215], v[114:117]
	v_mfma_f32_16x16x32_bf16 v[102:105], v[196:199], v[220:223], v[102:105]
	v_mfma_f32_16x16x32_bf16 v[98:101], v[204:207], v[220:223], v[98:101]
	v_mfma_f32_16x16x32_bf16 v[86:89], v[196:199], v[228:231], v[86:89]
	v_mfma_f32_16x16x32_bf16 v[82:85], v[204:207], v[228:231], v[82:85]
	v_mfma_f32_16x16x32_bf16 v[70:73], v[196:199], v[236:239], v[70:73]
	v_mfma_f32_16x16x32_bf16 v[66:69], v[204:207], v[236:239], v[66:69]
	v_mfma_f32_16x16x32_bf16 v[118:121], v[200:203], v[216:219], v[118:121]
	v_mfma_f32_16x16x32_bf16 v[114:117], v[208:211], v[216:219], v[114:117]
	v_mfma_f32_16x16x32_bf16 v[102:105], v[200:203], v[224:227], v[102:105]
	v_mfma_f32_16x16x32_bf16 v[98:101], v[208:211], v[224:227], v[98:101]
	v_mfma_f32_16x16x32_bf16 v[86:89], v[200:203], v[232:235], v[86:89]
	v_mfma_f32_16x16x32_bf16 v[82:85], v[208:211], v[232:235], v[82:85]
	v_mfma_f32_16x16x32_bf16 v[70:73], v[200:203], v[240:243], v[70:73]
	v_mfma_f32_16x16x32_bf16 v[66:69], v[208:211], v[240:243], v[66:69]
	s_setprio 0
	s_barrier
	s_add_i32 s60, s55, s44
	v_lshl_add_u64 v[156:157], s[36:37], 0, v[132:133]
	s_mov_b32 m0, s60
	ds_read_b128 v[212:215], v175 offset:16384
	ds_read_b128 v[216:219], v175 offset:17408
	ds_read_b128 v[220:223], v175 offset:18432
	ds_read_b128 v[224:227], v175 offset:19456
	ds_read_b128 v[228:231], v175 offset:20480
	ds_read_b128 v[232:235], v175 offset:21504
	ds_read_b128 v[236:239], v175 offset:22528
	ds_read_b128 v[240:243], v175 offset:23552
	global_load_lds_dwordx4 v[156:157], off
	s_add_i32 m0, s60, 0x2000
	s_add_u32 s60, s36, 0x40000
	v_lshl_add_u64 v[160:161], s[36:37], 0, v[136:137]
	s_addc_u32 s61, s37, 0
	s_add_i32 s62, s56, s44
	global_load_lds_dwordx4 v[160:161], off
	v_lshl_add_u64 v[176:177], s[60:61], 0, v[132:133]
	s_mov_b32 m0, s62
	v_lshl_add_u64 v[244:245], s[38:39], 0, v[134:135]
	global_load_lds_dwordx4 v[176:177], off
	v_lshl_add_u64 v[176:177], s[60:61], 0, v[136:137]
	s_add_i32 m0, s62, 0x2000
	s_nop 0
	global_load_lds_dwordx4 v[176:177], off
	v_lshl_add_u64 v[176:177], s[38:39], 0, v[130:131]
	s_mov_b32 m0, s45
	s_nop 0
	global_load_lds_dwordx4 v[176:177], off
	s_waitcnt vmcnt(7)
	s_waitcnt lgkmcnt(0)
	v_mfma_f32_16x16x32_bf16 v[62:65], v[180:183], v[212:215], v[62:65]
	v_mfma_f32_16x16x32_bf16 v[58:61], v[188:191], v[212:215], v[58:61]
	v_mfma_f32_16x16x32_bf16 v[46:49], v[180:183], v[220:223], v[46:49]
	v_mfma_f32_16x16x32_bf16 v[42:45], v[188:191], v[220:223], v[42:45]
	s_barrier
	s_setprio 1
	v_mfma_f32_16x16x32_bf16 v[30:33], v[180:183], v[228:231], v[30:33]
	v_mfma_f32_16x16x32_bf16 v[26:29], v[188:191], v[228:231], v[26:29]
	v_mfma_f32_16x16x32_bf16 v[14:17], v[180:183], v[236:239], v[14:17]
	v_mfma_f32_16x16x32_bf16 v[10:13], v[188:191], v[236:239], v[10:13]
	v_mfma_f32_16x16x32_bf16 v[62:65], v[184:187], v[216:219], v[62:65]
	v_mfma_f32_16x16x32_bf16 v[58:61], v[192:195], v[216:219], v[58:61]
	v_mfma_f32_16x16x32_bf16 v[46:49], v[184:187], v[224:227], v[46:49]
	v_mfma_f32_16x16x32_bf16 v[42:45], v[192:195], v[224:227], v[42:45]
	v_mfma_f32_16x16x32_bf16 v[30:33], v[184:187], v[232:235], v[30:33]
	v_mfma_f32_16x16x32_bf16 v[26:29], v[192:195], v[232:235], v[26:29]
	v_mfma_f32_16x16x32_bf16 v[14:17], v[184:187], v[240:243], v[14:17]
	v_mfma_f32_16x16x32_bf16 v[10:13], v[192:195], v[240:243], v[10:13]
	v_mfma_f32_16x16x32_bf16 v[54:57], v[196:199], v[212:215], v[54:57]
	v_mfma_f32_16x16x32_bf16 v[50:53], v[204:207], v[212:215], v[50:53]
	v_mfma_f32_16x16x32_bf16 v[38:41], v[196:199], v[220:223], v[38:41]
	v_mfma_f32_16x16x32_bf16 v[34:37], v[204:207], v[220:223], v[34:37]
	v_mfma_f32_16x16x32_bf16 v[22:25], v[196:199], v[228:231], v[22:25]
	v_mfma_f32_16x16x32_bf16 v[18:21], v[204:207], v[228:231], v[18:21]
	v_mfma_f32_16x16x32_bf16 v[6:9], v[196:199], v[236:239], v[6:9]
	v_mfma_f32_16x16x32_bf16 v[2:5], v[204:207], v[236:239], v[2:5]
	v_mfma_f32_16x16x32_bf16 v[54:57], v[200:203], v[216:219], v[54:57]
	v_mfma_f32_16x16x32_bf16 v[50:53], v[208:211], v[216:219], v[50:53]
	v_mfma_f32_16x16x32_bf16 v[38:41], v[200:203], v[224:227], v[38:41]
	v_mfma_f32_16x16x32_bf16 v[34:37], v[208:211], v[224:227], v[34:37]
	v_mfma_f32_16x16x32_bf16 v[22:25], v[200:203], v[232:235], v[22:25]
	v_mfma_f32_16x16x32_bf16 v[18:21], v[208:211], v[232:235], v[18:21]
	v_mfma_f32_16x16x32_bf16 v[6:9], v[200:203], v[240:243], v[6:9]
	v_mfma_f32_16x16x32_bf16 v[2:5], v[208:211], v[240:243], v[2:5]
	s_setprio 0
	s_barrier
	s_mov_b32 m0, s46
	s_nop 0
	global_load_lds_dwordx4 v134, s[38:39]
	s_add_i32 s60, 0, 0x18000
	v_add_u32_e32 v149, s60, v171
	s_add_i32 s61, 0, 0x1c000
	ds_read_b128 v[180:183], v149
	ds_read_b128 v[184:187], v149 offset:1024
	ds_read_b128 v[188:191], v149 offset:2048
	ds_read_b128 v[192:195], v149 offset:3072
	v_add_u32_e32 v149, s61, v171
	ds_read_b128 v[196:199], v149
	ds_read_b128 v[200:203], v149 offset:1024
	ds_read_b128 v[204:207], v149 offset:2048
	ds_read_b128 v[208:211], v149 offset:3072
	s_add_u32 s38, s38, 0x40000
	s_addc_u32 s39, s39, 0
	s_mov_b32 m0, s47
	v_lshl_add_u64 v[246:247], s[38:39], 0, v[130:131]
	ds_read_b128 v[212:215], v175 offset:32768
	ds_read_b128 v[216:219], v175 offset:33792
	ds_read_b128 v[220:223], v175 offset:34816
	ds_read_b128 v[224:227], v175 offset:35840
	ds_read_b128 v[228:231], v175 offset:36864
	ds_read_b128 v[232:235], v175 offset:37888
	ds_read_b128 v[236:239], v175 offset:38912
	ds_read_b128 v[240:243], v175 offset:39936
	global_load_lds_dwordx4 v[246:247], off
	v_lshl_add_u64 v[246:247], s[38:39], 0, v[134:135]
	s_mov_b32 m0, s48
	s_nop 0
	global_load_lds_dwordx4 v[246:247], off
	s_waitcnt vmcnt(8)
	s_waitcnt lgkmcnt(0)
	v_mfma_f32_16x16x32_bf16 v[126:129], v[180:183], v[212:215], v[126:129]
	v_mfma_f32_16x16x32_bf16 v[122:125], v[188:191], v[212:215], v[122:125]
	v_mfma_f32_16x16x32_bf16 v[110:113], v[180:183], v[220:223], v[110:113]
	v_mfma_f32_16x16x32_bf16 v[106:109], v[188:191], v[220:223], v[106:109]
	s_barrier
	s_setprio 1
	v_mfma_f32_16x16x32_bf16 v[94:97], v[180:183], v[228:231], v[94:97]
	v_mfma_f32_16x16x32_bf16 v[90:93], v[188:191], v[228:231], v[90:93]
	v_mfma_f32_16x16x32_bf16 v[78:81], v[180:183], v[236:239], v[78:81]
	v_mfma_f32_16x16x32_bf16 v[74:77], v[188:191], v[236:239], v[74:77]
	v_mfma_f32_16x16x32_bf16 v[126:129], v[184:187], v[216:219], v[126:129]
	v_mfma_f32_16x16x32_bf16 v[122:125], v[192:195], v[216:219], v[122:125]
	v_mfma_f32_16x16x32_bf16 v[110:113], v[184:187], v[224:227], v[110:113]
	v_mfma_f32_16x16x32_bf16 v[106:109], v[192:195], v[224:227], v[106:109]
	v_mfma_f32_16x16x32_bf16 v[94:97], v[184:187], v[232:235], v[94:97]
	v_mfma_f32_16x16x32_bf16 v[90:93], v[192:195], v[232:235], v[90:93]
	v_mfma_f32_16x16x32_bf16 v[78:81], v[184:187], v[240:243], v[78:81]
	v_mfma_f32_16x16x32_bf16 v[74:77], v[192:195], v[240:243], v[74:77]
	v_mfma_f32_16x16x32_bf16 v[118:121], v[196:199], v[212:215], v[118:121]
	v_mfma_f32_16x16x32_bf16 v[114:117], v[204:207], v[212:215], v[114:117]
	v_mfma_f32_16x16x32_bf16 v[102:105], v[196:199], v[220:223], v[102:105]
	v_mfma_f32_16x16x32_bf16 v[98:101], v[204:207], v[220:223], v[98:101]
	v_mfma_f32_16x16x32_bf16 v[86:89], v[196:199], v[228:231], v[86:89]
	v_mfma_f32_16x16x32_bf16 v[82:85], v[204:207], v[228:231], v[82:85]
	v_mfma_f32_16x16x32_bf16 v[70:73], v[196:199], v[236:239], v[70:73]
	v_mfma_f32_16x16x32_bf16 v[66:69], v[204:207], v[236:239], v[66:69]
	v_mfma_f32_16x16x32_bf16 v[118:121], v[200:203], v[216:219], v[118:121]
	v_mfma_f32_16x16x32_bf16 v[114:117], v[208:211], v[216:219], v[114:117]
	v_mfma_f32_16x16x32_bf16 v[102:105], v[200:203], v[224:227], v[102:105]
	v_mfma_f32_16x16x32_bf16 v[98:101], v[208:211], v[224:227], v[98:101]
	v_mfma_f32_16x16x32_bf16 v[86:89], v[200:203], v[232:235], v[86:89]
	v_mfma_f32_16x16x32_bf16 v[82:85], v[208:211], v[232:235], v[82:85]
	v_mfma_f32_16x16x32_bf16 v[70:73], v[200:203], v[240:243], v[70:73]
	v_mfma_f32_16x16x32_bf16 v[66:69], v[208:211], v[240:243], v[66:69]
	s_setprio 0
	s_barrier
	s_add_i32 s38, s60, s44
	v_lshl_add_u64 v[156:157], v[156:157], 0, s[18:19]
	s_mov_b32 m0, s38
	ds_read_b128 v[212:215], v175 offset:49152
	ds_read_b128 v[216:219], v175 offset:50176
	ds_read_b128 v[220:223], v175 offset:51200
	ds_read_b128 v[224:227], v175 offset:52224
	ds_read_b128 v[228:231], v175 offset:53248
	ds_read_b128 v[232:235], v175 offset:54272
	ds_read_b128 v[236:239], v175 offset:55296
	ds_read_b128 v[240:243], v175 offset:56320
	global_load_lds_dwordx4 v[156:157], off
	s_add_i32 m0, s38, 0x2000
	s_add_u32 s36, s36, 0x40080
	v_lshl_add_u64 v[156:157], v[160:161], 0, s[18:19]
	s_addc_u32 s37, s37, 0
	s_add_i32 s38, s61, s44
	global_load_lds_dwordx4 v[156:157], off
	v_lshl_add_u64 v[156:157], s[36:37], 0, v[132:133]
	s_mov_b32 m0, s38
	s_nop 0
	global_load_lds_dwordx4 v[156:157], off
	v_lshl_add_u64 v[156:157], s[36:37], 0, v[136:137]
	s_add_i32 m0, s38, 0x2000
	s_nop 0
	global_load_lds_dwordx4 v[156:157], off
	v_lshl_add_u64 v[156:157], v[176:177], 0, s[18:19]
	s_mov_b32 m0, s51
	s_nop 0
	global_load_lds_dwordx4 v[156:157], off
	s_waitcnt vmcnt(7)
	s_waitcnt lgkmcnt(0)
	v_mfma_f32_16x16x32_bf16 v[62:65], v[180:183], v[212:215], v[62:65]
	v_mfma_f32_16x16x32_bf16 v[58:61], v[188:191], v[212:215], v[58:61]
	v_mfma_f32_16x16x32_bf16 v[46:49], v[180:183], v[220:223], v[46:49]
	v_mfma_f32_16x16x32_bf16 v[42:45], v[188:191], v[220:223], v[42:45]
	s_barrier
	s_setprio 1
	v_mfma_f32_16x16x32_bf16 v[30:33], v[180:183], v[228:231], v[30:33]
	v_mfma_f32_16x16x32_bf16 v[26:29], v[188:191], v[228:231], v[26:29]
	v_mfma_f32_16x16x32_bf16 v[14:17], v[180:183], v[236:239], v[14:17]
	v_mfma_f32_16x16x32_bf16 v[10:13], v[188:191], v[236:239], v[10:13]
	v_mfma_f32_16x16x32_bf16 v[62:65], v[184:187], v[216:219], v[62:65]
	v_mfma_f32_16x16x32_bf16 v[58:61], v[192:195], v[216:219], v[58:61]
	v_mfma_f32_16x16x32_bf16 v[46:49], v[184:187], v[224:227], v[46:49]
	v_mfma_f32_16x16x32_bf16 v[42:45], v[192:195], v[224:227], v[42:45]
	v_mfma_f32_16x16x32_bf16 v[30:33], v[184:187], v[232:235], v[30:33]
	v_mfma_f32_16x16x32_bf16 v[26:29], v[192:195], v[232:235], v[26:29]
	v_mfma_f32_16x16x32_bf16 v[14:17], v[184:187], v[240:243], v[14:17]
	v_mfma_f32_16x16x32_bf16 v[10:13], v[192:195], v[240:243], v[10:13]
	v_mfma_f32_16x16x32_bf16 v[54:57], v[196:199], v[212:215], v[54:57]
	v_mfma_f32_16x16x32_bf16 v[50:53], v[204:207], v[212:215], v[50:53]
	v_mfma_f32_16x16x32_bf16 v[38:41], v[196:199], v[220:223], v[38:41]
	v_mfma_f32_16x16x32_bf16 v[34:37], v[204:207], v[220:223], v[34:37]
	v_mfma_f32_16x16x32_bf16 v[22:25], v[196:199], v[228:231], v[22:25]
	v_mfma_f32_16x16x32_bf16 v[18:21], v[204:207], v[228:231], v[18:21]
	v_mfma_f32_16x16x32_bf16 v[6:9], v[196:199], v[236:239], v[6:9]
	v_mfma_f32_16x16x32_bf16 v[2:5], v[204:207], v[236:239], v[2:5]
	v_mfma_f32_16x16x32_bf16 v[54:57], v[200:203], v[216:219], v[54:57]
	v_mfma_f32_16x16x32_bf16 v[50:53], v[208:211], v[216:219], v[50:53]
	v_mfma_f32_16x16x32_bf16 v[38:41], v[200:203], v[224:227], v[38:41]
	v_mfma_f32_16x16x32_bf16 v[34:37], v[208:211], v[224:227], v[34:37]
	v_mfma_f32_16x16x32_bf16 v[22:25], v[200:203], v[232:235], v[22:25]
	v_mfma_f32_16x16x32_bf16 v[18:21], v[208:211], v[232:235], v[18:21]
	v_mfma_f32_16x16x32_bf16 v[6:9], v[200:203], v[240:243], v[6:9]
	v_mfma_f32_16x16x32_bf16 v[2:5], v[208:211], v[240:243], v[2:5]
	s_setprio 0
	s_barrier
	s_add_i32 s59, s59, 2
	s_add_u32 s27, s27, 0x100
	s_addc_u32 s58, s58, 0
	s_add_u32 s34, s34, 0x100
	s_addc_u32 s35, s35, 0
	s_cmp_gt_u32 s59, 13
	s_cbranch_scc0 .LBB0_219
	s_and_b64 vcc, exec, s[20:21]
	s_cbranch_vccz .LBB0_222
	s_barrier

.LBB0_681:
	s_add_u32 s98, s40, 0xfffc0000
	s_addc_u32 s99, s41, -1
	s_mov_b32 m0, s58
	s_nop 0
	global_load_lds_dwordx4 v138, s[98:99]
	v_add_u32_e32 v154, s62, v156
	ds_read_b128 v[130:133], v154
	ds_read_b128 v[150:153], v154 offset:1024
	ds_read_b128 v[160:163], v154 offset:2048
	ds_read_b128 v[164:167], v154 offset:3072
	v_add_u32_e32 v154, s63, v156
	ds_read_b128 v[168:171], v154
	ds_read_b128 v[172:175], v154 offset:1024
	ds_read_b128 v[180:183], v154 offset:2048
	ds_read_b128 v[184:187], v154 offset:3072
	s_add_u32 s42, s40, 0xfffc0080
	s_addc_u32 s43, s41, -1
	s_cmp_eq_u32 s68, 12
	s_cselect_b32 s45, s31, s43
	s_cselect_b32 s44, s39, s42
	s_cselect_b32 s43, s29, s67
	s_cselect_b32 s42, s65, s66
	v_lshl_add_u64 v[154:155], s[40:41], 0, v[144:145]
	s_add_i32 m0, s51, 0xc000
	ds_read_b128 v[188:191], v158
	ds_read_b128 v[192:195], v158 offset:1024
	ds_read_b128 v[196:199], v158 offset:2048
	ds_read_b128 v[200:203], v158 offset:3072
	ds_read_b128 v[204:207], v158 offset:4096
	ds_read_b128 v[208:211], v158 offset:5120
	ds_read_b128 v[212:215], v158 offset:6144
	ds_read_b128 v[216:219], v158 offset:7168
	global_load_lds_dwordx4 v[154:155], off
	v_lshl_add_u64 v[154:155], s[40:41], 0, v[142:143]
	s_add_i32 m0, s51, 0xe000
	s_nop 0
	global_load_lds_dwordx4 v[154:155], off
	s_waitcnt vmcnt(8)
	s_waitcnt lgkmcnt(0)
	v_mfma_f32_16x16x32_bf16 v[114:117], v[130:133], v[188:191], v[114:117]
	v_mfma_f32_16x16x32_bf16 v[118:121], v[160:163], v[188:191], v[118:121]
	v_mfma_f32_16x16x32_bf16 v[98:101], v[130:133], v[196:199], v[98:101]
	v_mfma_f32_16x16x32_bf16 v[102:105], v[160:163], v[196:199], v[102:105]
	s_barrier
	s_setprio 1
	v_mfma_f32_16x16x32_bf16 v[82:85], v[130:133], v[204:207], v[82:85]
	v_mfma_f32_16x16x32_bf16 v[86:89], v[160:163], v[204:207], v[86:89]
	v_mfma_f32_16x16x32_bf16 v[66:69], v[130:133], v[212:215], v[66:69]
	v_mfma_f32_16x16x32_bf16 v[70:73], v[160:163], v[212:215], v[70:73]
	v_mfma_f32_16x16x32_bf16 v[114:117], v[150:153], v[192:195], v[114:117]
	v_mfma_f32_16x16x32_bf16 v[118:121], v[164:167], v[192:195], v[118:121]
	v_mfma_f32_16x16x32_bf16 v[98:101], v[150:153], v[200:203], v[98:101]
	v_mfma_f32_16x16x32_bf16 v[102:105], v[164:167], v[200:203], v[102:105]
	v_mfma_f32_16x16x32_bf16 v[82:85], v[150:153], v[208:211], v[82:85]
	v_mfma_f32_16x16x32_bf16 v[86:89], v[164:167], v[208:211], v[86:89]
	v_mfma_f32_16x16x32_bf16 v[66:69], v[150:153], v[216:219], v[66:69]
	v_mfma_f32_16x16x32_bf16 v[70:73], v[164:167], v[216:219], v[70:73]
	v_mfma_f32_16x16x32_bf16 v[122:125], v[168:171], v[188:191], v[122:125]
	v_mfma_f32_16x16x32_bf16 v[126:129], v[180:183], v[188:191], v[126:129]
	v_mfma_f32_16x16x32_bf16 v[106:109], v[168:171], v[196:199], v[106:109]
	v_mfma_f32_16x16x32_bf16 v[110:113], v[180:183], v[196:199], v[110:113]
	v_mfma_f32_16x16x32_bf16 v[90:93], v[168:171], v[204:207], v[90:93]
	v_mfma_f32_16x16x32_bf16 v[94:97], v[180:183], v[204:207], v[94:97]
	v_mfma_f32_16x16x32_bf16 v[74:77], v[168:171], v[212:215], v[74:77]
	v_mfma_f32_16x16x32_bf16 v[78:81], v[180:183], v[212:215], v[78:81]
	v_mfma_f32_16x16x32_bf16 v[122:125], v[172:175], v[192:195], v[122:125]
	v_mfma_f32_16x16x32_bf16 v[126:129], v[184:187], v[192:195], v[126:129]
	v_mfma_f32_16x16x32_bf16 v[106:109], v[172:175], v[200:203], v[106:109]
	v_mfma_f32_16x16x32_bf16 v[110:113], v[184:187], v[200:203], v[110:113]
	v_mfma_f32_16x16x32_bf16 v[90:93], v[172:175], v[208:211], v[90:93]
	v_mfma_f32_16x16x32_bf16 v[94:97], v[184:187], v[208:211], v[94:97]
	v_mfma_f32_16x16x32_bf16 v[74:77], v[172:175], v[216:219], v[74:77]
	v_mfma_f32_16x16x32_bf16 v[78:81], v[184:187], v[216:219], v[78:81]
	s_setprio 0
	s_barrier
	s_add_i32 s69, s62, s50
	v_lshl_add_u64 v[154:155], s[42:43], 0, v[136:137]
	s_mov_b32 m0, s69
	ds_read_b128 v[188:191], v158 offset:16384
	ds_read_b128 v[192:195], v158 offset:17408
	ds_read_b128 v[196:199], v158 offset:18432
	ds_read_b128 v[200:203], v158 offset:19456
	ds_read_b128 v[204:207], v158 offset:20480
	ds_read_b128 v[208:211], v158 offset:21504
	ds_read_b128 v[212:215], v158 offset:22528
	ds_read_b128 v[216:219], v158 offset:23552
	global_load_lds_dwordx4 v[154:155], off
	s_add_i32 m0, s69, 0x2000
	s_add_u32 s70, s42, 0x40000
	v_lshl_add_u64 v[176:177], s[42:43], 0, v[140:141]
	s_addc_u32 s71, s43, 0
	s_add_i32 s69, s63, s50
	global_load_lds_dwordx4 v[176:177], off
	v_lshl_add_u64 v[220:221], s[70:71], 0, v[136:137]
	s_mov_b32 m0, s69
	v_lshl_add_u64 v[222:223], s[44:45], 0, v[138:139]
	global_load_lds_dwordx4 v[220:221], off
	v_lshl_add_u64 v[220:221], s[70:71], 0, v[140:141]
	s_add_i32 m0, s69, 0x2000
	s_nop 0
	global_load_lds_dwordx4 v[220:221], off
	v_lshl_add_u64 v[220:221], s[44:45], 0, v[134:135]
	s_mov_b32 m0, s51
	s_nop 0
	global_load_lds_dwordx4 v[220:221], off
	s_waitcnt vmcnt(7)
	s_waitcnt lgkmcnt(0)
	v_mfma_f32_16x16x32_bf16 v[50:53], v[130:133], v[188:191], v[50:53]
	v_mfma_f32_16x16x32_bf16 v[54:57], v[160:163], v[188:191], v[54:57]
	v_mfma_f32_16x16x32_bf16 v[26:29], v[130:133], v[196:199], v[26:29]
	v_mfma_f32_16x16x32_bf16 v[30:33], v[160:163], v[196:199], v[30:33]
	s_barrier
	s_setprio 1
	v_mfma_f32_16x16x32_bf16 v[18:21], v[130:133], v[204:207], v[18:21]
	v_mfma_f32_16x16x32_bf16 v[22:25], v[160:163], v[204:207], v[22:25]
	v_mfma_f32_16x16x32_bf16 v[2:5], v[130:133], v[212:215], v[2:5]
	v_mfma_f32_16x16x32_bf16 v[6:9], v[160:163], v[212:215], v[6:9]
	v_mfma_f32_16x16x32_bf16 v[50:53], v[150:153], v[192:195], v[50:53]
	v_mfma_f32_16x16x32_bf16 v[54:57], v[164:167], v[192:195], v[54:57]
	v_mfma_f32_16x16x32_bf16 v[26:29], v[150:153], v[200:203], v[26:29]
	v_mfma_f32_16x16x32_bf16 v[30:33], v[164:167], v[200:203], v[30:33]
	v_mfma_f32_16x16x32_bf16 v[18:21], v[150:153], v[208:211], v[18:21]
	v_mfma_f32_16x16x32_bf16 v[22:25], v[164:167], v[208:211], v[22:25]
	v_mfma_f32_16x16x32_bf16 v[2:5], v[150:153], v[216:219], v[2:5]
	v_mfma_f32_16x16x32_bf16 v[6:9], v[164:167], v[216:219], v[6:9]
	v_mfma_f32_16x16x32_bf16 v[58:61], v[168:171], v[188:191], v[58:61]
	v_mfma_f32_16x16x32_bf16 v[62:65], v[180:183], v[188:191], v[62:65]
	v_mfma_f32_16x16x32_bf16 v[42:45], v[168:171], v[196:199], v[42:45]
	v_mfma_f32_16x16x32_bf16 v[46:49], v[180:183], v[196:199], v[46:49]
	v_mfma_f32_16x16x32_bf16 v[34:37], v[168:171], v[204:207], v[34:37]
	v_mfma_f32_16x16x32_bf16 v[38:41], v[180:183], v[204:207], v[38:41]
	v_mfma_f32_16x16x32_bf16 v[10:13], v[168:171], v[212:215], v[10:13]
	v_mfma_f32_16x16x32_bf16 v[14:17], v[180:183], v[212:215], v[14:17]
	v_mfma_f32_16x16x32_bf16 v[58:61], v[172:175], v[192:195], v[58:61]
	v_mfma_f32_16x16x32_bf16 v[62:65], v[184:187], v[192:195], v[62:65]
	v_mfma_f32_16x16x32_bf16 v[42:45], v[172:175], v[200:203], v[42:45]
	v_mfma_f32_16x16x32_bf16 v[46:49], v[184:187], v[200:203], v[46:49]
	v_mfma_f32_16x16x32_bf16 v[34:37], v[172:175], v[208:211], v[34:37]
	v_mfma_f32_16x16x32_bf16 v[38:41], v[184:187], v[208:211], v[38:41]
	v_mfma_f32_16x16x32_bf16 v[10:13], v[172:175], v[216:219], v[10:13]
	v_mfma_f32_16x16x32_bf16 v[14:17], v[184:187], v[216:219], v[14:17]
	s_setprio 0
	s_barrier
	s_mov_b32 m0, s52
	s_nop 0
	global_load_lds_dwordx4 v138, s[44:45]
	s_add_i32 s69, 0, 0x18000
	s_add_i32 s70, 0, 0x1c000
	v_add_u32_e32 v164, s69, v156
	v_add_u32_e32 v179, s70, v156
	ds_read_b128 v[130:133], v164
	ds_read_b128 v[150:153], v164 offset:1024
	ds_read_b128 v[160:163], v164 offset:2048
	ds_read_b128 v[164:167], v164 offset:3072
	ds_read_b128 v[168:171], v179
	ds_read_b128 v[172:175], v179 offset:1024
	ds_read_b128 v[180:183], v179 offset:2048
	ds_read_b128 v[184:187], v179 offset:3072
	s_add_u32 s44, s44, 0x40000
	s_addc_u32 s45, s45, 0
	s_mov_b32 m0, s53
	v_lshl_add_u64 v[224:225], s[44:45], 0, v[134:135]
	ds_read_b128 v[188:191], v158 offset:32768
	ds_read_b128 v[192:195], v158 offset:33792
	ds_read_b128 v[196:199], v158 offset:34816
	ds_read_b128 v[200:203], v158 offset:35840
	ds_read_b128 v[204:207], v158 offset:36864
	ds_read_b128 v[208:211], v158 offset:37888
	ds_read_b128 v[212:215], v158 offset:38912
	ds_read_b128 v[216:219], v158 offset:39936
	global_load_lds_dwordx4 v[224:225], off
	v_lshl_add_u64 v[224:225], s[44:45], 0, v[138:139]
	s_mov_b32 m0, s54
	s_nop 0
	global_load_lds_dwordx4 v[224:225], off
	s_waitcnt vmcnt(8)
	s_waitcnt lgkmcnt(0)
	v_mfma_f32_16x16x32_bf16 v[114:117], v[130:133], v[188:191], v[114:117]
	v_mfma_f32_16x16x32_bf16 v[118:121], v[160:163], v[188:191], v[118:121]
	v_mfma_f32_16x16x32_bf16 v[98:101], v[130:133], v[196:199], v[98:101]
	v_mfma_f32_16x16x32_bf16 v[102:105], v[160:163], v[196:199], v[102:105]
	s_barrier
	s_setprio 1
	v_mfma_f32_16x16x32_bf16 v[82:85], v[130:133], v[204:207], v[82:85]
	v_mfma_f32_16x16x32_bf16 v[86:89], v[160:163], v[204:207], v[86:89]
	v_mfma_f32_16x16x32_bf16 v[66:69], v[130:133], v[212:215], v[66:69]
	v_mfma_f32_16x16x32_bf16 v[70:73], v[160:163], v[212:215], v[70:73]
	v_mfma_f32_16x16x32_bf16 v[114:117], v[150:153], v[192:195], v[114:117]
	v_mfma_f32_16x16x32_bf16 v[118:121], v[164:167], v[192:195], v[118:121]
	v_mfma_f32_16x16x32_bf16 v[98:101], v[150:153], v[200:203], v[98:101]
	v_mfma_f32_16x16x32_bf16 v[102:105], v[164:167], v[200:203], v[102:105]
	v_mfma_f32_16x16x32_bf16 v[82:85], v[150:153], v[208:211], v[82:85]
	v_mfma_f32_16x16x32_bf16 v[86:89], v[164:167], v[208:211], v[86:89]
	v_mfma_f32_16x16x32_bf16 v[66:69], v[150:153], v[216:219], v[66:69]
	v_mfma_f32_16x16x32_bf16 v[70:73], v[164:167], v[216:219], v[70:73]
	v_mfma_f32_16x16x32_bf16 v[122:125], v[168:171], v[188:191], v[122:125]
	v_mfma_f32_16x16x32_bf16 v[126:129], v[180:183], v[188:191], v[126:129]
	v_mfma_f32_16x16x32_bf16 v[106:109], v[168:171], v[196:199], v[106:109]
	v_mfma_f32_16x16x32_bf16 v[110:113], v[180:183], v[196:199], v[110:113]
	v_mfma_f32_16x16x32_bf16 v[90:93], v[168:171], v[204:207], v[90:93]
	v_mfma_f32_16x16x32_bf16 v[94:97], v[180:183], v[204:207], v[94:97]
	v_mfma_f32_16x16x32_bf16 v[74:77], v[168:171], v[212:215], v[74:77]
	v_mfma_f32_16x16x32_bf16 v[78:81], v[180:183], v[212:215], v[78:81]
	v_mfma_f32_16x16x32_bf16 v[122:125], v[172:175], v[192:195], v[122:125]
	v_mfma_f32_16x16x32_bf16 v[126:129], v[184:187], v[192:195], v[126:129]
	v_mfma_f32_16x16x32_bf16 v[106:109], v[172:175], v[200:203], v[106:109]
	v_mfma_f32_16x16x32_bf16 v[110:113], v[184:187], v[200:203], v[110:113]
	v_mfma_f32_16x16x32_bf16 v[90:93], v[172:175], v[208:211], v[90:93]
	v_mfma_f32_16x16x32_bf16 v[94:97], v[184:187], v[208:211], v[94:97]
	v_mfma_f32_16x16x32_bf16 v[74:77], v[172:175], v[216:219], v[74:77]
	v_mfma_f32_16x16x32_bf16 v[78:81], v[184:187], v[216:219], v[78:81]
	s_setprio 0
	s_barrier
	s_add_i32 s44, s69, s50
	v_lshl_add_u64 v[154:155], v[154:155], 0, s[22:23]
	s_mov_b32 m0, s44
	ds_read_b128 v[188:191], v158 offset:49152
	ds_read_b128 v[192:195], v158 offset:50176
	ds_read_b128 v[196:199], v158 offset:51200
	ds_read_b128 v[200:203], v158 offset:52224
	ds_read_b128 v[204:207], v158 offset:53248
	ds_read_b128 v[208:211], v158 offset:54272
	ds_read_b128 v[212:215], v158 offset:55296
	ds_read_b128 v[216:219], v158 offset:56320
	global_load_lds_dwordx4 v[154:155], off
	s_add_i32 m0, s44, 0x2000
	s_add_u32 s42, s42, 0x40080
	v_lshl_add_u64 v[154:155], v[176:177], 0, s[22:23]
	s_addc_u32 s43, s43, 0
	s_add_i32 s44, s70, s50
	global_load_lds_dwordx4 v[154:155], off
	v_lshl_add_u64 v[154:155], s[42:43], 0, v[136:137]
	s_mov_b32 m0, s44
	s_nop 0
	global_load_lds_dwordx4 v[154:155], off
	v_lshl_add_u64 v[154:155], s[42:43], 0, v[140:141]
	s_add_i32 m0, s44, 0x2000
	s_nop 0
	global_load_lds_dwordx4 v[154:155], off
	v_lshl_add_u64 v[154:155], v[220:221], 0, s[22:23]
	s_mov_b32 m0, s57
	s_nop 0
	global_load_lds_dwordx4 v[154:155], off
	s_waitcnt vmcnt(7)
	s_waitcnt lgkmcnt(0)
	v_mfma_f32_16x16x32_bf16 v[50:53], v[130:133], v[188:191], v[50:53]
	v_mfma_f32_16x16x32_bf16 v[54:57], v[160:163], v[188:191], v[54:57]
	v_mfma_f32_16x16x32_bf16 v[26:29], v[130:133], v[196:199], v[26:29]
	v_mfma_f32_16x16x32_bf16 v[30:33], v[160:163], v[196:199], v[30:33]
	s_barrier
	s_setprio 1
	v_mfma_f32_16x16x32_bf16 v[18:21], v[130:133], v[204:207], v[18:21]
	v_mfma_f32_16x16x32_bf16 v[22:25], v[160:163], v[204:207], v[22:25]
	v_mfma_f32_16x16x32_bf16 v[2:5], v[130:133], v[212:215], v[2:5]
	v_mfma_f32_16x16x32_bf16 v[6:9], v[160:163], v[212:215], v[6:9]
	v_mfma_f32_16x16x32_bf16 v[50:53], v[150:153], v[192:195], v[50:53]
	v_mfma_f32_16x16x32_bf16 v[54:57], v[164:167], v[192:195], v[54:57]
	v_mfma_f32_16x16x32_bf16 v[26:29], v[150:153], v[200:203], v[26:29]
	v_mfma_f32_16x16x32_bf16 v[30:33], v[164:167], v[200:203], v[30:33]
	v_mfma_f32_16x16x32_bf16 v[18:21], v[150:153], v[208:211], v[18:21]
	v_mfma_f32_16x16x32_bf16 v[22:25], v[164:167], v[208:211], v[22:25]
	v_mfma_f32_16x16x32_bf16 v[2:5], v[150:153], v[216:219], v[2:5]
	v_mfma_f32_16x16x32_bf16 v[6:9], v[164:167], v[216:219], v[6:9]
	v_mfma_f32_16x16x32_bf16 v[58:61], v[168:171], v[188:191], v[58:61]
	v_mfma_f32_16x16x32_bf16 v[62:65], v[180:183], v[188:191], v[62:65]
	v_mfma_f32_16x16x32_bf16 v[42:45], v[168:171], v[196:199], v[42:45]
	v_mfma_f32_16x16x32_bf16 v[46:49], v[180:183], v[196:199], v[46:49]
	v_mfma_f32_16x16x32_bf16 v[34:37], v[168:171], v[204:207], v[34:37]
	v_mfma_f32_16x16x32_bf16 v[38:41], v[180:183], v[204:207], v[38:41]
	v_mfma_f32_16x16x32_bf16 v[10:13], v[168:171], v[212:215], v[10:13]
	v_mfma_f32_16x16x32_bf16 v[14:17], v[180:183], v[212:215], v[14:17]
	v_mfma_f32_16x16x32_bf16 v[58:61], v[172:175], v[192:195], v[58:61]
	v_mfma_f32_16x16x32_bf16 v[62:65], v[184:187], v[192:195], v[62:65]
	v_mfma_f32_16x16x32_bf16 v[42:45], v[172:175], v[200:203], v[42:45]
	v_mfma_f32_16x16x32_bf16 v[46:49], v[184:187], v[200:203], v[46:49]
	v_mfma_f32_16x16x32_bf16 v[34:37], v[172:175], v[208:211], v[34:37]
	v_mfma_f32_16x16x32_bf16 v[38:41], v[184:187], v[208:211], v[38:41]
	v_mfma_f32_16x16x32_bf16 v[10:13], v[172:175], v[216:219], v[10:13]
	v_mfma_f32_16x16x32_bf16 v[14:17], v[184:187], v[216:219], v[14:17]
	s_setprio 0
	s_barrier
	s_add_i32 s68, s68, 2
	s_add_u32 s66, s66, 0x100
	s_addc_u32 s67, s67, 0
	s_add_u32 s40, s40, 0x100
	s_addc_u32 s41, s41, 0
	s_cmp_gt_u32 s68, 13
	s_cbranch_scc0 .LBB0_681
	s_and_b64 vcc, exec, s[24:25]
	s_cbranch_vccz .LBB0_684
	s_barrier

.LBB0_858:
	s_add_u32 s98, s36, 0xfffc0000
	s_addc_u32 s99, s37, -1
	s_mov_b32 m0, s52
	s_nop 0
	global_load_lds_dwordx4 v134, s[98:99]
	ds_read_b128 v[164:167], v173
	ds_read_b128 v[180:183], v173 offset:1024
	ds_read_b128 v[184:187], v173 offset:2048
	ds_read_b128 v[188:191], v173 offset:3072
	ds_read_b128 v[192:195], v174
	ds_read_b128 v[196:199], v174 offset:1024
	ds_read_b128 v[200:203], v174 offset:2048
	ds_read_b128 v[204:207], v174 offset:3072
	s_add_u32 s38, s36, 0xfffc0080
	s_addc_u32 s39, s37, -1
	s_cmp_eq_u32 s61, 12
	s_cselect_b32 s41, s25, s39
	s_cselect_b32 s40, s31, s38
	s_cselect_b32 s39, s23, s60
	s_cselect_b32 s38, s58, s59
	v_lshl_add_u64 v[176:177], s[36:37], 0, v[142:143]
	s_add_i32 m0, s35, 0xc000
	ds_read_b128 v[208:211], v175
	ds_read_b128 v[212:215], v175 offset:1024
	ds_read_b128 v[216:219], v175 offset:2048
	ds_read_b128 v[220:223], v175 offset:3072
	ds_read_b128 v[224:227], v175 offset:4096
	ds_read_b128 v[228:231], v175 offset:5120
	ds_read_b128 v[232:235], v175 offset:6144
	ds_read_b128 v[236:239], v175 offset:7168
	global_load_lds_dwordx4 v[176:177], off
	v_lshl_add_u64 v[176:177], s[36:37], 0, v[140:141]
	s_add_i32 m0, s35, 0xe000
	s_nop 0
	global_load_lds_dwordx4 v[176:177], off
	s_waitcnt vmcnt(8)
	s_waitcnt lgkmcnt(0)
	v_mfma_f32_16x16x32_bf16 v[126:129], v[164:167], v[208:211], v[126:129]
	v_mfma_f32_16x16x32_bf16 v[122:125], v[184:187], v[208:211], v[122:125]
	v_mfma_f32_16x16x32_bf16 v[110:113], v[164:167], v[216:219], v[110:113]
	v_mfma_f32_16x16x32_bf16 v[106:109], v[184:187], v[216:219], v[106:109]
	s_barrier
	s_setprio 1
	v_mfma_f32_16x16x32_bf16 v[94:97], v[164:167], v[224:227], v[94:97]
	v_mfma_f32_16x16x32_bf16 v[90:93], v[184:187], v[224:227], v[90:93]
	v_mfma_f32_16x16x32_bf16 v[78:81], v[164:167], v[232:235], v[78:81]
	v_mfma_f32_16x16x32_bf16 v[74:77], v[184:187], v[232:235], v[74:77]
	v_mfma_f32_16x16x32_bf16 v[126:129], v[180:183], v[212:215], v[126:129]
	v_mfma_f32_16x16x32_bf16 v[122:125], v[188:191], v[212:215], v[122:125]
	v_mfma_f32_16x16x32_bf16 v[110:113], v[180:183], v[220:223], v[110:113]
	v_mfma_f32_16x16x32_bf16 v[106:109], v[188:191], v[220:223], v[106:109]
	v_mfma_f32_16x16x32_bf16 v[94:97], v[180:183], v[228:231], v[94:97]
	v_mfma_f32_16x16x32_bf16 v[90:93], v[188:191], v[228:231], v[90:93]
	v_mfma_f32_16x16x32_bf16 v[78:81], v[180:183], v[236:239], v[78:81]
	v_mfma_f32_16x16x32_bf16 v[74:77], v[188:191], v[236:239], v[74:77]
	v_mfma_f32_16x16x32_bf16 v[118:121], v[192:195], v[208:211], v[118:121]
	v_mfma_f32_16x16x32_bf16 v[114:117], v[200:203], v[208:211], v[114:117]
	v_mfma_f32_16x16x32_bf16 v[102:105], v[192:195], v[216:219], v[102:105]
	v_mfma_f32_16x16x32_bf16 v[98:101], v[200:203], v[216:219], v[98:101]
	v_mfma_f32_16x16x32_bf16 v[86:89], v[192:195], v[224:227], v[86:89]
	v_mfma_f32_16x16x32_bf16 v[82:85], v[200:203], v[224:227], v[82:85]
	v_mfma_f32_16x16x32_bf16 v[70:73], v[192:195], v[232:235], v[70:73]
	v_mfma_f32_16x16x32_bf16 v[66:69], v[200:203], v[232:235], v[66:69]
	v_mfma_f32_16x16x32_bf16 v[118:121], v[196:199], v[212:215], v[118:121]
	v_mfma_f32_16x16x32_bf16 v[114:117], v[204:207], v[212:215], v[114:117]
	v_mfma_f32_16x16x32_bf16 v[102:105], v[196:199], v[220:223], v[102:105]
	v_mfma_f32_16x16x32_bf16 v[98:101], v[204:207], v[220:223], v[98:101]
	v_mfma_f32_16x16x32_bf16 v[86:89], v[196:199], v[228:231], v[86:89]
	v_mfma_f32_16x16x32_bf16 v[82:85], v[204:207], v[228:231], v[82:85]
	v_mfma_f32_16x16x32_bf16 v[70:73], v[196:199], v[236:239], v[70:73]
	v_mfma_f32_16x16x32_bf16 v[66:69], v[204:207], v[236:239], v[66:69]
	s_setprio 0
	s_barrier
	s_add_i32 s62, s56, s45
	v_lshl_add_u64 v[176:177], s[38:39], 0, v[132:133]
	s_mov_b32 m0, s62
	ds_read_b128 v[208:211], v175 offset:16384
	ds_read_b128 v[212:215], v175 offset:17408
	ds_read_b128 v[216:219], v175 offset:18432
	ds_read_b128 v[220:223], v175 offset:19456
	ds_read_b128 v[224:227], v175 offset:20480
	ds_read_b128 v[228:231], v175 offset:21504
	ds_read_b128 v[232:235], v175 offset:22528
	ds_read_b128 v[236:239], v175 offset:23552
	global_load_lds_dwordx4 v[176:177], off
	s_add_i32 m0, s62, 0x2000
	s_add_u32 s62, s38, 0x40000
	v_lshl_add_u64 v[240:241], s[38:39], 0, v[136:137]
	s_addc_u32 s63, s39, 0
	s_add_i32 s64, s57, s45
	global_load_lds_dwordx4 v[240:241], off
	v_lshl_add_u64 v[242:243], s[62:63], 0, v[132:133]
	s_mov_b32 m0, s64
	v_lshl_add_u64 v[244:245], s[40:41], 0, v[134:135]
	global_load_lds_dwordx4 v[242:243], off
	v_lshl_add_u64 v[242:243], s[62:63], 0, v[136:137]
	s_add_i32 m0, s64, 0x2000
	s_nop 0
	global_load_lds_dwordx4 v[242:243], off
	v_lshl_add_u64 v[242:243], s[40:41], 0, v[130:131]
	s_mov_b32 m0, s35
	s_nop 0
	global_load_lds_dwordx4 v[242:243], off
	s_waitcnt vmcnt(7)
	s_waitcnt lgkmcnt(0)
	v_mfma_f32_16x16x32_bf16 v[62:65], v[164:167], v[208:211], v[62:65]
	v_mfma_f32_16x16x32_bf16 v[58:61], v[184:187], v[208:211], v[58:61]
	v_mfma_f32_16x16x32_bf16 v[46:49], v[164:167], v[216:219], v[46:49]
	v_mfma_f32_16x16x32_bf16 v[42:45], v[184:187], v[216:219], v[42:45]
	s_barrier
	s_setprio 1
	v_mfma_f32_16x16x32_bf16 v[30:33], v[164:167], v[224:227], v[30:33]
	v_mfma_f32_16x16x32_bf16 v[26:29], v[184:187], v[224:227], v[26:29]
	v_mfma_f32_16x16x32_bf16 v[14:17], v[164:167], v[232:235], v[14:17]
	v_mfma_f32_16x16x32_bf16 v[10:13], v[184:187], v[232:235], v[10:13]
	v_mfma_f32_16x16x32_bf16 v[62:65], v[180:183], v[212:215], v[62:65]
	v_mfma_f32_16x16x32_bf16 v[58:61], v[188:191], v[212:215], v[58:61]
	v_mfma_f32_16x16x32_bf16 v[46:49], v[180:183], v[220:223], v[46:49]
	v_mfma_f32_16x16x32_bf16 v[42:45], v[188:191], v[220:223], v[42:45]
	v_mfma_f32_16x16x32_bf16 v[30:33], v[180:183], v[228:231], v[30:33]
	v_mfma_f32_16x16x32_bf16 v[26:29], v[188:191], v[228:231], v[26:29]
	v_mfma_f32_16x16x32_bf16 v[14:17], v[180:183], v[236:239], v[14:17]
	v_mfma_f32_16x16x32_bf16 v[10:13], v[188:191], v[236:239], v[10:13]
	v_mfma_f32_16x16x32_bf16 v[54:57], v[192:195], v[208:211], v[54:57]
	v_mfma_f32_16x16x32_bf16 v[50:53], v[200:203], v[208:211], v[50:53]
	v_mfma_f32_16x16x32_bf16 v[38:41], v[192:195], v[216:219], v[38:41]
	v_mfma_f32_16x16x32_bf16 v[34:37], v[200:203], v[216:219], v[34:37]
	v_mfma_f32_16x16x32_bf16 v[22:25], v[192:195], v[224:227], v[22:25]
	v_mfma_f32_16x16x32_bf16 v[18:21], v[200:203], v[224:227], v[18:21]
	v_mfma_f32_16x16x32_bf16 v[6:9], v[192:195], v[232:235], v[6:9]
	v_mfma_f32_16x16x32_bf16 v[2:5], v[200:203], v[232:235], v[2:5]
	v_mfma_f32_16x16x32_bf16 v[54:57], v[196:199], v[212:215], v[54:57]
	v_mfma_f32_16x16x32_bf16 v[50:53], v[204:207], v[212:215], v[50:53]
	v_mfma_f32_16x16x32_bf16 v[38:41], v[196:199], v[220:223], v[38:41]
	v_mfma_f32_16x16x32_bf16 v[34:37], v[204:207], v[220:223], v[34:37]
	v_mfma_f32_16x16x32_bf16 v[22:25], v[196:199], v[228:231], v[22:25]
	v_mfma_f32_16x16x32_bf16 v[18:21], v[204:207], v[228:231], v[18:21]
	v_mfma_f32_16x16x32_bf16 v[6:9], v[196:199], v[236:239], v[6:9]
	v_mfma_f32_16x16x32_bf16 v[2:5], v[204:207], v[236:239], v[2:5]
	s_setprio 0
	s_barrier
	s_mov_b32 m0, s46
	s_nop 0
	global_load_lds_dwordx4 v134, s[40:41]
	s_add_i32 s62, 0, 0x18000
	v_add_u32_e32 v149, s62, v171
	s_add_i32 s63, 0, 0x1c000
	ds_read_b128 v[164:167], v149
	ds_read_b128 v[180:183], v149 offset:1024
	ds_read_b128 v[184:187], v149 offset:2048
	ds_read_b128 v[188:191], v149 offset:3072
	v_add_u32_e32 v149, s63, v171
	ds_read_b128 v[192:195], v149
	ds_read_b128 v[196:199], v149 offset:1024
	ds_read_b128 v[200:203], v149 offset:2048
	ds_read_b128 v[204:207], v149 offset:3072
	s_add_u32 s40, s40, 0x40000
	s_addc_u32 s41, s41, 0
	s_mov_b32 m0, s47
	v_lshl_add_u64 v[246:247], s[40:41], 0, v[130:131]
	ds_read_b128 v[208:211], v175 offset:32768
	ds_read_b128 v[212:215], v175 offset:33792
	ds_read_b128 v[216:219], v175 offset:34816
	ds_read_b128 v[220:223], v175 offset:35840
	ds_read_b128 v[224:227], v175 offset:36864
	ds_read_b128 v[228:231], v175 offset:37888
	ds_read_b128 v[232:235], v175 offset:38912
	ds_read_b128 v[236:239], v175 offset:39936
	global_load_lds_dwordx4 v[246:247], off
	v_lshl_add_u64 v[246:247], s[40:41], 0, v[134:135]
	s_mov_b32 m0, s48
	s_nop 0
	global_load_lds_dwordx4 v[246:247], off
	s_waitcnt vmcnt(8)
	s_waitcnt lgkmcnt(0)
	v_mfma_f32_16x16x32_bf16 v[126:129], v[164:167], v[208:211], v[126:129]
	v_mfma_f32_16x16x32_bf16 v[122:125], v[184:187], v[208:211], v[122:125]
	v_mfma_f32_16x16x32_bf16 v[110:113], v[164:167], v[216:219], v[110:113]
	v_mfma_f32_16x16x32_bf16 v[106:109], v[184:187], v[216:219], v[106:109]
	s_barrier
	s_setprio 1
	v_mfma_f32_16x16x32_bf16 v[94:97], v[164:167], v[224:227], v[94:97]
	v_mfma_f32_16x16x32_bf16 v[90:93], v[184:187], v[224:227], v[90:93]
	v_mfma_f32_16x16x32_bf16 v[78:81], v[164:167], v[232:235], v[78:81]
	v_mfma_f32_16x16x32_bf16 v[74:77], v[184:187], v[232:235], v[74:77]
	v_mfma_f32_16x16x32_bf16 v[126:129], v[180:183], v[212:215], v[126:129]
	v_mfma_f32_16x16x32_bf16 v[122:125], v[188:191], v[212:215], v[122:125]
	v_mfma_f32_16x16x32_bf16 v[110:113], v[180:183], v[220:223], v[110:113]
	v_mfma_f32_16x16x32_bf16 v[106:109], v[188:191], v[220:223], v[106:109]
	v_mfma_f32_16x16x32_bf16 v[94:97], v[180:183], v[228:231], v[94:97]
	v_mfma_f32_16x16x32_bf16 v[90:93], v[188:191], v[228:231], v[90:93]
	v_mfma_f32_16x16x32_bf16 v[78:81], v[180:183], v[236:239], v[78:81]
	v_mfma_f32_16x16x32_bf16 v[74:77], v[188:191], v[236:239], v[74:77]
	v_mfma_f32_16x16x32_bf16 v[118:121], v[192:195], v[208:211], v[118:121]
	v_mfma_f32_16x16x32_bf16 v[114:117], v[200:203], v[208:211], v[114:117]
	v_mfma_f32_16x16x32_bf16 v[102:105], v[192:195], v[216:219], v[102:105]
	v_mfma_f32_16x16x32_bf16 v[98:101], v[200:203], v[216:219], v[98:101]
	v_mfma_f32_16x16x32_bf16 v[86:89], v[192:195], v[224:227], v[86:89]
	v_mfma_f32_16x16x32_bf16 v[82:85], v[200:203], v[224:227], v[82:85]
	v_mfma_f32_16x16x32_bf16 v[70:73], v[192:195], v[232:235], v[70:73]
	v_mfma_f32_16x16x32_bf16 v[66:69], v[200:203], v[232:235], v[66:69]
	v_mfma_f32_16x16x32_bf16 v[118:121], v[196:199], v[212:215], v[118:121]
	v_mfma_f32_16x16x32_bf16 v[114:117], v[204:207], v[212:215], v[114:117]
	v_mfma_f32_16x16x32_bf16 v[102:105], v[196:199], v[220:223], v[102:105]
	v_mfma_f32_16x16x32_bf16 v[98:101], v[204:207], v[220:223], v[98:101]
	v_mfma_f32_16x16x32_bf16 v[86:89], v[196:199], v[228:231], v[86:89]
	v_mfma_f32_16x16x32_bf16 v[82:85], v[204:207], v[228:231], v[82:85]
	v_mfma_f32_16x16x32_bf16 v[70:73], v[196:199], v[236:239], v[70:73]
	v_mfma_f32_16x16x32_bf16 v[66:69], v[204:207], v[236:239], v[66:69]
	s_setprio 0
	s_barrier
	s_add_i32 s40, s62, s45
	v_lshl_add_u64 v[176:177], v[176:177], 0, s[8:9]
	s_mov_b32 m0, s40
	ds_read_b128 v[208:211], v175 offset:49152
	ds_read_b128 v[212:215], v175 offset:50176
	ds_read_b128 v[216:219], v175 offset:51200
	ds_read_b128 v[220:223], v175 offset:52224
	ds_read_b128 v[224:227], v175 offset:53248
	ds_read_b128 v[228:231], v175 offset:54272
	ds_read_b128 v[232:235], v175 offset:55296
	ds_read_b128 v[236:239], v175 offset:56320
	global_load_lds_dwordx4 v[176:177], off
	s_add_i32 m0, s40, 0x2000
	s_add_u32 s38, s38, 0x40080
	v_lshl_add_u64 v[176:177], v[240:241], 0, s[8:9]
	s_addc_u32 s39, s39, 0
	s_add_i32 s40, s63, s45
	global_load_lds_dwordx4 v[176:177], off
	v_lshl_add_u64 v[176:177], s[38:39], 0, v[132:133]
	s_mov_b32 m0, s40
	s_nop 0
	global_load_lds_dwordx4 v[176:177], off
	v_lshl_add_u64 v[176:177], s[38:39], 0, v[136:137]
	s_add_i32 m0, s40, 0x2000
	s_nop 0
	global_load_lds_dwordx4 v[176:177], off
	v_lshl_add_u64 v[176:177], v[242:243], 0, s[8:9]
	s_mov_b32 m0, s51
	s_nop 0
	global_load_lds_dwordx4 v[176:177], off
	s_waitcnt vmcnt(7)
	s_waitcnt lgkmcnt(0)
	v_mfma_f32_16x16x32_bf16 v[62:65], v[164:167], v[208:211], v[62:65]
	v_mfma_f32_16x16x32_bf16 v[58:61], v[184:187], v[208:211], v[58:61]
	v_mfma_f32_16x16x32_bf16 v[46:49], v[164:167], v[216:219], v[46:49]
	v_mfma_f32_16x16x32_bf16 v[42:45], v[184:187], v[216:219], v[42:45]
	s_barrier
	s_setprio 1
	v_mfma_f32_16x16x32_bf16 v[30:33], v[164:167], v[224:227], v[30:33]
	v_mfma_f32_16x16x32_bf16 v[26:29], v[184:187], v[224:227], v[26:29]
	v_mfma_f32_16x16x32_bf16 v[14:17], v[164:167], v[232:235], v[14:17]
	v_mfma_f32_16x16x32_bf16 v[10:13], v[184:187], v[232:235], v[10:13]
	v_mfma_f32_16x16x32_bf16 v[62:65], v[180:183], v[212:215], v[62:65]
	v_mfma_f32_16x16x32_bf16 v[58:61], v[188:191], v[212:215], v[58:61]
	v_mfma_f32_16x16x32_bf16 v[46:49], v[180:183], v[220:223], v[46:49]
	v_mfma_f32_16x16x32_bf16 v[42:45], v[188:191], v[220:223], v[42:45]
	v_mfma_f32_16x16x32_bf16 v[30:33], v[180:183], v[228:231], v[30:33]
	v_mfma_f32_16x16x32_bf16 v[26:29], v[188:191], v[228:231], v[26:29]
	v_mfma_f32_16x16x32_bf16 v[14:17], v[180:183], v[236:239], v[14:17]
	v_mfma_f32_16x16x32_bf16 v[10:13], v[188:191], v[236:239], v[10:13]
	v_mfma_f32_16x16x32_bf16 v[54:57], v[192:195], v[208:211], v[54:57]
	v_mfma_f32_16x16x32_bf16 v[50:53], v[200:203], v[208:211], v[50:53]
	v_mfma_f32_16x16x32_bf16 v[38:41], v[192:195], v[216:219], v[38:41]
	v_mfma_f32_16x16x32_bf16 v[34:37], v[200:203], v[216:219], v[34:37]
	v_mfma_f32_16x16x32_bf16 v[22:25], v[192:195], v[224:227], v[22:25]
	v_mfma_f32_16x16x32_bf16 v[18:21], v[200:203], v[224:227], v[18:21]
	v_mfma_f32_16x16x32_bf16 v[6:9], v[192:195], v[232:235], v[6:9]
	v_mfma_f32_16x16x32_bf16 v[2:5], v[200:203], v[232:235], v[2:5]
	v_mfma_f32_16x16x32_bf16 v[54:57], v[196:199], v[212:215], v[54:57]
	v_mfma_f32_16x16x32_bf16 v[50:53], v[204:207], v[212:215], v[50:53]
	v_mfma_f32_16x16x32_bf16 v[38:41], v[196:199], v[220:223], v[38:41]
	v_mfma_f32_16x16x32_bf16 v[34:37], v[204:207], v[220:223], v[34:37]
	v_mfma_f32_16x16x32_bf16 v[22:25], v[196:199], v[228:231], v[22:25]
	v_mfma_f32_16x16x32_bf16 v[18:21], v[204:207], v[228:231], v[18:21]
	v_mfma_f32_16x16x32_bf16 v[6:9], v[196:199], v[236:239], v[6:9]
	v_mfma_f32_16x16x32_bf16 v[2:5], v[204:207], v[236:239], v[2:5]
	s_setprio 0
	s_barrier
	s_add_i32 s61, s61, 2
	s_add_u32 s59, s59, 0x100
	s_addc_u32 s60, s60, 0
	s_add_u32 s36, s36, 0x100
	s_addc_u32 s37, s37, 0
	s_cmp_gt_u32 s61, 13
	s_cbranch_scc0 .LBB0_858
	s_andn2_b64 vcc, exec, s[2:3]
	s_cbranch_vccnz .Lrs8h_skip1
	v_lshl_add_u32 v188, s24, 8, v170
	v_ashrrev_i32_e32 v189, 31, v188
	v_lshlrev_b64 v[180:181], 6, v[188:189]
	v_lshl_add_u64 v[196:197], v[138:139], 0, v[180:181]
	v_or_b32_e32 v180, 16, v188
	v_or_b32_e32 v190, 32, v188
	v_or_b32_e32 v188, 48, v188
	v_ashrrev_i32_e32 v181, 31, v180
	v_ashrrev_i32_e32 v191, 31, v190
	v_ashrrev_i32_e32 v189, 31, v188
	v_lshlrev_b64 v[180:181], 6, v[180:181]
	v_lshlrev_b64 v[190:191], 6, v[190:191]
	v_lshlrev_b64 v[188:189], 6, v[188:189]
	v_add_co_u32_e32 v208, vcc, s49, v196
	v_lshl_add_u64 v[184:185], v[138:139], 0, v[180:181]
	v_lshl_add_u64 v[190:191], v[138:139], 0, v[190:191]
	v_lshl_add_u64 v[192:193], v[138:139], 0, v[188:189]
	v_addc_co_u32_e32 v209, vcc, 0, v197, vcc
	flat_load_dwordx4 v[180:183], v[196:197]
	s_nop 0
	flat_load_dwordx4 v[184:187], v[184:185]
	s_nop 0
	flat_load_dwordx4 v[188:191], v[190:191]
	s_nop 0
	flat_load_dwordx4 v[192:195], v[192:193]
	s_nop 0
	flat_load_dwordx4 v[196:199], v[208:209]
	flat_load_dwordx4 v[200:203], v[208:209] offset:1024
	flat_load_dwordx4 v[204:207], v[208:209] offset:2048
	s_nop 0
	flat_load_dwordx4 v[208:211], v[208:209] offset:3072

.LBB0_1039:
	s_add_u32 s98, s40, 0xfff00000
	s_addc_u32 s99, s41, -1
	s_mov_b32 m0, s58
	s_nop 0
	global_load_lds_dwordx4 v138, s[98:99]
	v_add_u32_e32 v154, s62, v156
	ds_read_b128 v[130:133], v154
	ds_read_b128 v[150:153], v154 offset:1024
	ds_read_b128 v[160:163], v154 offset:2048
	ds_read_b128 v[164:167], v154 offset:3072
	v_add_u32_e32 v154, s63, v156
	ds_read_b128 v[168:171], v154
	ds_read_b128 v[172:175], v154 offset:1024
	ds_read_b128 v[180:183], v154 offset:2048
	ds_read_b128 v[184:187], v154 offset:3072
	s_add_u32 s42, s40, 0xfff00080
	s_addc_u32 s43, s41, -1
	s_cmp_eq_u32 s68, 60
	s_cselect_b32 s45, s31, s43
	s_cselect_b32 s44, s39, s42
	s_cselect_b32 s43, s29, s67
	s_cselect_b32 s42, s65, s66
	v_lshl_add_u64 v[154:155], s[40:41], 0, v[144:145]
	s_add_i32 m0, s51, 0xc000
	ds_read_b128 v[188:191], v158
	ds_read_b128 v[192:195], v158 offset:1024
	ds_read_b128 v[196:199], v158 offset:2048
	ds_read_b128 v[200:203], v158 offset:3072
	ds_read_b128 v[204:207], v158 offset:4096
	ds_read_b128 v[208:211], v158 offset:5120
	ds_read_b128 v[212:215], v158 offset:6144
	ds_read_b128 v[216:219], v158 offset:7168
	global_load_lds_dwordx4 v[154:155], off
	v_lshl_add_u64 v[154:155], s[40:41], 0, v[142:143]
	s_add_i32 m0, s51, 0xe000
	s_nop 0
	global_load_lds_dwordx4 v[154:155], off
	s_waitcnt vmcnt(8)
	s_waitcnt lgkmcnt(0)
	v_mfma_f32_16x16x32_bf16 v[114:117], v[130:133], v[188:191], v[114:117]
	v_mfma_f32_16x16x32_bf16 v[118:121], v[160:163], v[188:191], v[118:121]
	v_mfma_f32_16x16x32_bf16 v[98:101], v[130:133], v[196:199], v[98:101]
	v_mfma_f32_16x16x32_bf16 v[102:105], v[160:163], v[196:199], v[102:105]
	s_barrier
	s_setprio 1
	v_mfma_f32_16x16x32_bf16 v[82:85], v[130:133], v[204:207], v[82:85]
	v_mfma_f32_16x16x32_bf16 v[86:89], v[160:163], v[204:207], v[86:89]
	v_mfma_f32_16x16x32_bf16 v[66:69], v[130:133], v[212:215], v[66:69]
	v_mfma_f32_16x16x32_bf16 v[70:73], v[160:163], v[212:215], v[70:73]
	v_mfma_f32_16x16x32_bf16 v[114:117], v[150:153], v[192:195], v[114:117]
	v_mfma_f32_16x16x32_bf16 v[118:121], v[164:167], v[192:195], v[118:121]
	v_mfma_f32_16x16x32_bf16 v[98:101], v[150:153], v[200:203], v[98:101]
	v_mfma_f32_16x16x32_bf16 v[102:105], v[164:167], v[200:203], v[102:105]
	v_mfma_f32_16x16x32_bf16 v[82:85], v[150:153], v[208:211], v[82:85]
	v_mfma_f32_16x16x32_bf16 v[86:89], v[164:167], v[208:211], v[86:89]
	v_mfma_f32_16x16x32_bf16 v[66:69], v[150:153], v[216:219], v[66:69]
	v_mfma_f32_16x16x32_bf16 v[70:73], v[164:167], v[216:219], v[70:73]
	v_mfma_f32_16x16x32_bf16 v[122:125], v[168:171], v[188:191], v[122:125]
	v_mfma_f32_16x16x32_bf16 v[126:129], v[180:183], v[188:191], v[126:129]
	v_mfma_f32_16x16x32_bf16 v[106:109], v[168:171], v[196:199], v[106:109]
	v_mfma_f32_16x16x32_bf16 v[110:113], v[180:183], v[196:199], v[110:113]
	v_mfma_f32_16x16x32_bf16 v[90:93], v[168:171], v[204:207], v[90:93]
	v_mfma_f32_16x16x32_bf16 v[94:97], v[180:183], v[204:207], v[94:97]
	v_mfma_f32_16x16x32_bf16 v[74:77], v[168:171], v[212:215], v[74:77]
	v_mfma_f32_16x16x32_bf16 v[78:81], v[180:183], v[212:215], v[78:81]
	v_mfma_f32_16x16x32_bf16 v[122:125], v[172:175], v[192:195], v[122:125]
	v_mfma_f32_16x16x32_bf16 v[126:129], v[184:187], v[192:195], v[126:129]
	v_mfma_f32_16x16x32_bf16 v[106:109], v[172:175], v[200:203], v[106:109]
	v_mfma_f32_16x16x32_bf16 v[110:113], v[184:187], v[200:203], v[110:113]
	v_mfma_f32_16x16x32_bf16 v[90:93], v[172:175], v[208:211], v[90:93]
	v_mfma_f32_16x16x32_bf16 v[94:97], v[184:187], v[208:211], v[94:97]
	v_mfma_f32_16x16x32_bf16 v[74:77], v[172:175], v[216:219], v[74:77]
	v_mfma_f32_16x16x32_bf16 v[78:81], v[184:187], v[216:219], v[78:81]
	s_setprio 0
	s_barrier
	s_add_i32 s69, s62, s50
	v_lshl_add_u64 v[154:155], s[42:43], 0, v[136:137]
	s_mov_b32 m0, s69
	ds_read_b128 v[188:191], v158 offset:16384
	ds_read_b128 v[192:195], v158 offset:17408
	ds_read_b128 v[196:199], v158 offset:18432
	ds_read_b128 v[200:203], v158 offset:19456
	ds_read_b128 v[204:207], v158 offset:20480
	ds_read_b128 v[208:211], v158 offset:21504
	ds_read_b128 v[212:215], v158 offset:22528
	ds_read_b128 v[216:219], v158 offset:23552
	global_load_lds_dwordx4 v[154:155], off
	s_add_i32 m0, s69, 0x2000
	s_add_u32 s70, s42, 0x100000
	v_lshl_add_u64 v[176:177], s[42:43], 0, v[140:141]
	s_addc_u32 s71, s43, 0
	s_add_i32 s69, s63, s50
	global_load_lds_dwordx4 v[176:177], off
	v_lshl_add_u64 v[220:221], s[70:71], 0, v[136:137]
	s_mov_b32 m0, s69
	v_lshl_add_u64 v[222:223], s[44:45], 0, v[138:139]
	global_load_lds_dwordx4 v[220:221], off
	v_lshl_add_u64 v[220:221], s[70:71], 0, v[140:141]
	s_add_i32 m0, s69, 0x2000
	s_nop 0
	global_load_lds_dwordx4 v[220:221], off
	v_lshl_add_u64 v[220:221], s[44:45], 0, v[134:135]
	s_mov_b32 m0, s51
	s_nop 0
	global_load_lds_dwordx4 v[220:221], off
	s_waitcnt vmcnt(7)
	s_waitcnt lgkmcnt(0)
	v_mfma_f32_16x16x32_bf16 v[50:53], v[130:133], v[188:191], v[50:53]
	v_mfma_f32_16x16x32_bf16 v[54:57], v[160:163], v[188:191], v[54:57]
	v_mfma_f32_16x16x32_bf16 v[26:29], v[130:133], v[196:199], v[26:29]
	v_mfma_f32_16x16x32_bf16 v[30:33], v[160:163], v[196:199], v[30:33]
	s_barrier
	s_setprio 1
	v_mfma_f32_16x16x32_bf16 v[18:21], v[130:133], v[204:207], v[18:21]
	v_mfma_f32_16x16x32_bf16 v[22:25], v[160:163], v[204:207], v[22:25]
	v_mfma_f32_16x16x32_bf16 v[2:5], v[130:133], v[212:215], v[2:5]
	v_mfma_f32_16x16x32_bf16 v[6:9], v[160:163], v[212:215], v[6:9]
	v_mfma_f32_16x16x32_bf16 v[50:53], v[150:153], v[192:195], v[50:53]
	v_mfma_f32_16x16x32_bf16 v[54:57], v[164:167], v[192:195], v[54:57]
	v_mfma_f32_16x16x32_bf16 v[26:29], v[150:153], v[200:203], v[26:29]
	v_mfma_f32_16x16x32_bf16 v[30:33], v[164:167], v[200:203], v[30:33]
	v_mfma_f32_16x16x32_bf16 v[18:21], v[150:153], v[208:211], v[18:21]
	v_mfma_f32_16x16x32_bf16 v[22:25], v[164:167], v[208:211], v[22:25]
	v_mfma_f32_16x16x32_bf16 v[2:5], v[150:153], v[216:219], v[2:5]
	v_mfma_f32_16x16x32_bf16 v[6:9], v[164:167], v[216:219], v[6:9]
	v_mfma_f32_16x16x32_bf16 v[58:61], v[168:171], v[188:191], v[58:61]
	v_mfma_f32_16x16x32_bf16 v[62:65], v[180:183], v[188:191], v[62:65]
	v_mfma_f32_16x16x32_bf16 v[42:45], v[168:171], v[196:199], v[42:45]
	v_mfma_f32_16x16x32_bf16 v[46:49], v[180:183], v[196:199], v[46:49]
	v_mfma_f32_16x16x32_bf16 v[34:37], v[168:171], v[204:207], v[34:37]
	v_mfma_f32_16x16x32_bf16 v[38:41], v[180:183], v[204:207], v[38:41]
	v_mfma_f32_16x16x32_bf16 v[10:13], v[168:171], v[212:215], v[10:13]
	v_mfma_f32_16x16x32_bf16 v[14:17], v[180:183], v[212:215], v[14:17]
	v_mfma_f32_16x16x32_bf16 v[58:61], v[172:175], v[192:195], v[58:61]
	v_mfma_f32_16x16x32_bf16 v[62:65], v[184:187], v[192:195], v[62:65]
	v_mfma_f32_16x16x32_bf16 v[42:45], v[172:175], v[200:203], v[42:45]
	v_mfma_f32_16x16x32_bf16 v[46:49], v[184:187], v[200:203], v[46:49]
	v_mfma_f32_16x16x32_bf16 v[34:37], v[172:175], v[208:211], v[34:37]
	v_mfma_f32_16x16x32_bf16 v[38:41], v[184:187], v[208:211], v[38:41]
	v_mfma_f32_16x16x32_bf16 v[10:13], v[172:175], v[216:219], v[10:13]
	v_mfma_f32_16x16x32_bf16 v[14:17], v[184:187], v[216:219], v[14:17]
	s_setprio 0
	s_barrier
	s_mov_b32 m0, s52
	s_nop 0
	global_load_lds_dwordx4 v138, s[44:45]
	s_add_i32 s69, 0, 0x18000
	s_add_i32 s70, 0, 0x1c000
	v_add_u32_e32 v164, s69, v156
	v_add_u32_e32 v179, s70, v156
	ds_read_b128 v[130:133], v164
	ds_read_b128 v[150:153], v164 offset:1024
	ds_read_b128 v[160:163], v164 offset:2048
	ds_read_b128 v[164:167], v164 offset:3072
	ds_read_b128 v[168:171], v179
	ds_read_b128 v[172:175], v179 offset:1024
	ds_read_b128 v[180:183], v179 offset:2048
	ds_read_b128 v[184:187], v179 offset:3072
	s_add_u32 s44, s44, 0x100000
	s_addc_u32 s45, s45, 0
	s_mov_b32 m0, s53
	v_lshl_add_u64 v[224:225], s[44:45], 0, v[134:135]
	ds_read_b128 v[188:191], v158 offset:32768
	ds_read_b128 v[192:195], v158 offset:33792
	ds_read_b128 v[196:199], v158 offset:34816
	ds_read_b128 v[200:203], v158 offset:35840
	ds_read_b128 v[204:207], v158 offset:36864
	ds_read_b128 v[208:211], v158 offset:37888
	ds_read_b128 v[212:215], v158 offset:38912
	ds_read_b128 v[216:219], v158 offset:39936
	global_load_lds_dwordx4 v[224:225], off
	v_lshl_add_u64 v[224:225], s[44:45], 0, v[138:139]
	s_mov_b32 m0, s54
	s_nop 0
	global_load_lds_dwordx4 v[224:225], off
	s_waitcnt vmcnt(8)
	s_waitcnt lgkmcnt(0)
	v_mfma_f32_16x16x32_bf16 v[114:117], v[130:133], v[188:191], v[114:117]
	v_mfma_f32_16x16x32_bf16 v[118:121], v[160:163], v[188:191], v[118:121]
	v_mfma_f32_16x16x32_bf16 v[98:101], v[130:133], v[196:199], v[98:101]
	v_mfma_f32_16x16x32_bf16 v[102:105], v[160:163], v[196:199], v[102:105]
	s_barrier
	s_setprio 1
	v_mfma_f32_16x16x32_bf16 v[82:85], v[130:133], v[204:207], v[82:85]
	v_mfma_f32_16x16x32_bf16 v[86:89], v[160:163], v[204:207], v[86:89]
	v_mfma_f32_16x16x32_bf16 v[66:69], v[130:133], v[212:215], v[66:69]
	v_mfma_f32_16x16x32_bf16 v[70:73], v[160:163], v[212:215], v[70:73]
	v_mfma_f32_16x16x32_bf16 v[114:117], v[150:153], v[192:195], v[114:117]
	v_mfma_f32_16x16x32_bf16 v[118:121], v[164:167], v[192:195], v[118:121]
	v_mfma_f32_16x16x32_bf16 v[98:101], v[150:153], v[200:203], v[98:101]
	v_mfma_f32_16x16x32_bf16 v[102:105], v[164:167], v[200:203], v[102:105]
	v_mfma_f32_16x16x32_bf16 v[82:85], v[150:153], v[208:211], v[82:85]
	v_mfma_f32_16x16x32_bf16 v[86:89], v[164:167], v[208:211], v[86:89]
	v_mfma_f32_16x16x32_bf16 v[66:69], v[150:153], v[216:219], v[66:69]
	v_mfma_f32_16x16x32_bf16 v[70:73], v[164:167], v[216:219], v[70:73]
	v_mfma_f32_16x16x32_bf16 v[122:125], v[168:171], v[188:191], v[122:125]
	v_mfma_f32_16x16x32_bf16 v[126:129], v[180:183], v[188:191], v[126:129]
	v_mfma_f32_16x16x32_bf16 v[106:109], v[168:171], v[196:199], v[106:109]
	v_mfma_f32_16x16x32_bf16 v[110:113], v[180:183], v[196:199], v[110:113]
	v_mfma_f32_16x16x32_bf16 v[90:93], v[168:171], v[204:207], v[90:93]
	v_mfma_f32_16x16x32_bf16 v[94:97], v[180:183], v[204:207], v[94:97]
	v_mfma_f32_16x16x32_bf16 v[74:77], v[168:171], v[212:215], v[74:77]
	v_mfma_f32_16x16x32_bf16 v[78:81], v[180:183], v[212:215], v[78:81]
	v_mfma_f32_16x16x32_bf16 v[122:125], v[172:175], v[192:195], v[122:125]
	v_mfma_f32_16x16x32_bf16 v[126:129], v[184:187], v[192:195], v[126:129]
	v_mfma_f32_16x16x32_bf16 v[106:109], v[172:175], v[200:203], v[106:109]
	v_mfma_f32_16x16x32_bf16 v[110:113], v[184:187], v[200:203], v[110:113]
	v_mfma_f32_16x16x32_bf16 v[90:93], v[172:175], v[208:211], v[90:93]
	v_mfma_f32_16x16x32_bf16 v[94:97], v[184:187], v[208:211], v[94:97]
	v_mfma_f32_16x16x32_bf16 v[74:77], v[172:175], v[216:219], v[74:77]
	v_mfma_f32_16x16x32_bf16 v[78:81], v[184:187], v[216:219], v[78:81]
	s_setprio 0
	s_barrier
	s_add_i32 s44, s69, s50
	v_lshl_add_u64 v[154:155], v[154:155], 0, s[22:23]
	s_mov_b32 m0, s44
	ds_read_b128 v[188:191], v158 offset:49152
	ds_read_b128 v[192:195], v158 offset:50176
	ds_read_b128 v[196:199], v158 offset:51200
	ds_read_b128 v[200:203], v158 offset:52224
	ds_read_b128 v[204:207], v158 offset:53248
	ds_read_b128 v[208:211], v158 offset:54272
	ds_read_b128 v[212:215], v158 offset:55296
	ds_read_b128 v[216:219], v158 offset:56320
	global_load_lds_dwordx4 v[154:155], off
	s_add_i32 m0, s44, 0x2000
	s_add_u32 s42, s42, 0x100080
	v_lshl_add_u64 v[154:155], v[176:177], 0, s[22:23]
	s_addc_u32 s43, s43, 0
	s_add_i32 s44, s70, s50
	global_load_lds_dwordx4 v[154:155], off
	v_lshl_add_u64 v[154:155], s[42:43], 0, v[136:137]
	s_mov_b32 m0, s44
	s_nop 0
	global_load_lds_dwordx4 v[154:155], off
	v_lshl_add_u64 v[154:155], s[42:43], 0, v[140:141]
	s_add_i32 m0, s44, 0x2000
	s_nop 0
	global_load_lds_dwordx4 v[154:155], off
	v_lshl_add_u64 v[154:155], v[220:221], 0, s[22:23]
	s_mov_b32 m0, s57
	s_nop 0
	global_load_lds_dwordx4 v[154:155], off
	s_waitcnt vmcnt(7)
	s_waitcnt lgkmcnt(0)
	v_mfma_f32_16x16x32_bf16 v[50:53], v[130:133], v[188:191], v[50:53]
	v_mfma_f32_16x16x32_bf16 v[54:57], v[160:163], v[188:191], v[54:57]
	v_mfma_f32_16x16x32_bf16 v[26:29], v[130:133], v[196:199], v[26:29]
	v_mfma_f32_16x16x32_bf16 v[30:33], v[160:163], v[196:199], v[30:33]
	s_barrier
	s_setprio 1
	v_mfma_f32_16x16x32_bf16 v[18:21], v[130:133], v[204:207], v[18:21]
	v_mfma_f32_16x16x32_bf16 v[22:25], v[160:163], v[204:207], v[22:25]
	v_mfma_f32_16x16x32_bf16 v[2:5], v[130:133], v[212:215], v[2:5]
	v_mfma_f32_16x16x32_bf16 v[6:9], v[160:163], v[212:215], v[6:9]
	v_mfma_f32_16x16x32_bf16 v[50:53], v[150:153], v[192:195], v[50:53]
	v_mfma_f32_16x16x32_bf16 v[54:57], v[164:167], v[192:195], v[54:57]
	v_mfma_f32_16x16x32_bf16 v[26:29], v[150:153], v[200:203], v[26:29]
	v_mfma_f32_16x16x32_bf16 v[30:33], v[164:167], v[200:203], v[30:33]
	v_mfma_f32_16x16x32_bf16 v[18:21], v[150:153], v[208:211], v[18:21]
	v_mfma_f32_16x16x32_bf16 v[22:25], v[164:167], v[208:211], v[22:25]
	v_mfma_f32_16x16x32_bf16 v[2:5], v[150:153], v[216:219], v[2:5]
	v_mfma_f32_16x16x32_bf16 v[6:9], v[164:167], v[216:219], v[6:9]
	v_mfma_f32_16x16x32_bf16 v[58:61], v[168:171], v[188:191], v[58:61]
	v_mfma_f32_16x16x32_bf16 v[62:65], v[180:183], v[188:191], v[62:65]
	v_mfma_f32_16x16x32_bf16 v[42:45], v[168:171], v[196:199], v[42:45]
	v_mfma_f32_16x16x32_bf16 v[46:49], v[180:183], v[196:199], v[46:49]
	v_mfma_f32_16x16x32_bf16 v[34:37], v[168:171], v[204:207], v[34:37]
	v_mfma_f32_16x16x32_bf16 v[38:41], v[180:183], v[204:207], v[38:41]
	v_mfma_f32_16x16x32_bf16 v[10:13], v[168:171], v[212:215], v[10:13]
	v_mfma_f32_16x16x32_bf16 v[14:17], v[180:183], v[212:215], v[14:17]
	v_mfma_f32_16x16x32_bf16 v[58:61], v[172:175], v[192:195], v[58:61]
	v_mfma_f32_16x16x32_bf16 v[62:65], v[184:187], v[192:195], v[62:65]
	v_mfma_f32_16x16x32_bf16 v[42:45], v[172:175], v[200:203], v[42:45]
	v_mfma_f32_16x16x32_bf16 v[46:49], v[184:187], v[200:203], v[46:49]
	v_mfma_f32_16x16x32_bf16 v[34:37], v[172:175], v[208:211], v[34:37]
	v_mfma_f32_16x16x32_bf16 v[38:41], v[184:187], v[208:211], v[38:41]
	v_mfma_f32_16x16x32_bf16 v[10:13], v[172:175], v[216:219], v[10:13]
	v_mfma_f32_16x16x32_bf16 v[14:17], v[184:187], v[216:219], v[14:17]
	s_setprio 0
	s_barrier
	s_add_i32 s68, s68, 2
	s_add_u32 s66, s66, 0x100
	s_addc_u32 s67, s67, 0
	s_add_u32 s40, s40, 0x100
	s_addc_u32 s41, s41, 0
	s_cmp_gt_u32 s68, 61
	s_cbranch_scc0 .LBB0_1039
	s_and_b64 vcc, exec, s[24:25]
	s_cbranch_vccz .LBB0_1042
	s_barrier

.LBB0_1308:
	s_add_u32 s98, s36, 0xfffc0000
	s_addc_u32 s99, s37, -1
	s_mov_b32 m0, s51
	s_nop 0
	global_load_lds_dwordx4 v158, s[98:99]
	ds_read_b128 v[130:133], v184
	ds_read_b128 v[134:137], v184 offset:1024
	ds_read_b128 v[138:141], v184 offset:2048
	ds_read_b128 v[142:145], v184 offset:3072
	ds_read_b128 v[146:149], v185
	ds_read_b128 v[150:153], v185 offset:1024
	ds_read_b128 v[172:175], v185 offset:2048
	ds_read_b128 v[196:199], v185 offset:3072
	s_add_u32 s38, s36, 0xfffc0080
	s_addc_u32 s39, s37, -1
	s_cmp_eq_u32 s61, 12
	s_cselect_b32 s41, s27, s39
	s_cselect_b32 s40, s35, s38
	s_cselect_b32 s39, s25, s60
	s_cselect_b32 s38, s58, s59
	v_lshl_add_u64 v[176:177], s[36:37], 0, v[166:167]
	s_add_i32 m0, s45, 0xc000
	ds_read_b128 v[200:203], v186
	ds_read_b128 v[204:207], v186 offset:1024
	ds_read_b128 v[208:211], v186 offset:2048
	ds_read_b128 v[212:215], v186 offset:3072
	ds_read_b128 v[216:219], v186 offset:4096
	ds_read_b128 v[220:223], v186 offset:5120
	ds_read_b128 v[224:227], v186 offset:6144
	ds_read_b128 v[228:231], v186 offset:7168
	global_load_lds_dwordx4 v[176:177], off
	v_lshl_add_u64 v[176:177], s[36:37], 0, v[164:165]
	s_add_i32 m0, s45, 0xe000
	s_nop 0
	global_load_lds_dwordx4 v[176:177], off
	s_waitcnt vmcnt(8)
	s_waitcnt lgkmcnt(0)
	v_mfma_f32_16x16x32_bf16 v[126:129], v[130:133], v[200:203], v[126:129]
	v_mfma_f32_16x16x32_bf16 v[122:125], v[138:141], v[200:203], v[122:125]
	v_mfma_f32_16x16x32_bf16 v[110:113], v[130:133], v[208:211], v[110:113]
	v_mfma_f32_16x16x32_bf16 v[106:109], v[138:141], v[208:211], v[106:109]
	s_barrier
	s_setprio 1
	v_mfma_f32_16x16x32_bf16 v[94:97], v[130:133], v[216:219], v[94:97]
	v_mfma_f32_16x16x32_bf16 v[90:93], v[138:141], v[216:219], v[90:93]
	v_mfma_f32_16x16x32_bf16 v[78:81], v[130:133], v[224:227], v[78:81]
	v_mfma_f32_16x16x32_bf16 v[74:77], v[138:141], v[224:227], v[74:77]
	v_mfma_f32_16x16x32_bf16 v[126:129], v[134:137], v[204:207], v[126:129]
	v_mfma_f32_16x16x32_bf16 v[122:125], v[142:145], v[204:207], v[122:125]
	v_mfma_f32_16x16x32_bf16 v[110:113], v[134:137], v[212:215], v[110:113]
	v_mfma_f32_16x16x32_bf16 v[106:109], v[142:145], v[212:215], v[106:109]
	v_mfma_f32_16x16x32_bf16 v[94:97], v[134:137], v[220:223], v[94:97]
	v_mfma_f32_16x16x32_bf16 v[90:93], v[142:145], v[220:223], v[90:93]
	v_mfma_f32_16x16x32_bf16 v[78:81], v[134:137], v[228:231], v[78:81]
	v_mfma_f32_16x16x32_bf16 v[74:77], v[142:145], v[228:231], v[74:77]
	v_mfma_f32_16x16x32_bf16 v[118:121], v[146:149], v[200:203], v[118:121]
	v_mfma_f32_16x16x32_bf16 v[114:117], v[172:175], v[200:203], v[114:117]
	v_mfma_f32_16x16x32_bf16 v[102:105], v[146:149], v[208:211], v[102:105]
	v_mfma_f32_16x16x32_bf16 v[98:101], v[172:175], v[208:211], v[98:101]
	v_mfma_f32_16x16x32_bf16 v[86:89], v[146:149], v[216:219], v[86:89]
	v_mfma_f32_16x16x32_bf16 v[82:85], v[172:175], v[216:219], v[82:85]
	v_mfma_f32_16x16x32_bf16 v[70:73], v[146:149], v[224:227], v[70:73]
	v_mfma_f32_16x16x32_bf16 v[66:69], v[172:175], v[224:227], v[66:69]
	v_mfma_f32_16x16x32_bf16 v[118:121], v[150:153], v[204:207], v[118:121]
	v_mfma_f32_16x16x32_bf16 v[114:117], v[196:199], v[204:207], v[114:117]
	v_mfma_f32_16x16x32_bf16 v[102:105], v[150:153], v[212:215], v[102:105]
	v_mfma_f32_16x16x32_bf16 v[98:101], v[196:199], v[212:215], v[98:101]
	v_mfma_f32_16x16x32_bf16 v[86:89], v[150:153], v[220:223], v[86:89]
	v_mfma_f32_16x16x32_bf16 v[82:85], v[196:199], v[220:223], v[82:85]
	v_mfma_f32_16x16x32_bf16 v[70:73], v[150:153], v[228:231], v[70:73]
	v_mfma_f32_16x16x32_bf16 v[66:69], v[196:199], v[228:231], v[66:69]
	s_setprio 0
	s_barrier
	s_add_i32 s62, s55, s44
	v_lshl_add_u64 v[176:177], s[38:39], 0, v[156:157]
	s_mov_b32 m0, s62
	ds_read_b128 v[200:203], v186 offset:16384
	ds_read_b128 v[204:207], v186 offset:17408
	ds_read_b128 v[208:211], v186 offset:18432
	ds_read_b128 v[212:215], v186 offset:19456
	ds_read_b128 v[216:219], v186 offset:20480
	ds_read_b128 v[220:223], v186 offset:21504
	ds_read_b128 v[224:227], v186 offset:22528
	ds_read_b128 v[228:231], v186 offset:23552
	global_load_lds_dwordx4 v[176:177], off
	s_add_i32 m0, s62, 0x2000
	s_add_u32 s62, s38, 0x40000
	v_lshl_add_u64 v[232:233], s[38:39], 0, v[160:161]
	s_addc_u32 s63, s39, 0
	s_add_i32 s64, s56, s44
	global_load_lds_dwordx4 v[232:233], off
	v_lshl_add_u64 v[234:235], s[62:63], 0, v[156:157]
	s_mov_b32 m0, s64
	v_lshl_add_u64 v[236:237], s[40:41], 0, v[158:159]
	global_load_lds_dwordx4 v[234:235], off
	v_lshl_add_u64 v[234:235], s[62:63], 0, v[160:161]
	s_add_i32 m0, s64, 0x2000
	s_nop 0
	global_load_lds_dwordx4 v[234:235], off
	v_lshl_add_u64 v[234:235], s[40:41], 0, v[154:155]
	s_mov_b32 m0, s45
	s_nop 0
	global_load_lds_dwordx4 v[234:235], off
	s_waitcnt vmcnt(7)
	s_waitcnt lgkmcnt(0)
	v_mfma_f32_16x16x32_bf16 v[62:65], v[130:133], v[200:203], v[62:65]
	v_mfma_f32_16x16x32_bf16 v[58:61], v[138:141], v[200:203], v[58:61]
	v_mfma_f32_16x16x32_bf16 v[46:49], v[130:133], v[208:211], v[46:49]
	v_mfma_f32_16x16x32_bf16 v[42:45], v[138:141], v[208:211], v[42:45]
	s_barrier
	s_setprio 1
	v_mfma_f32_16x16x32_bf16 v[30:33], v[130:133], v[216:219], v[30:33]
	v_mfma_f32_16x16x32_bf16 v[26:29], v[138:141], v[216:219], v[26:29]
	v_mfma_f32_16x16x32_bf16 v[14:17], v[130:133], v[224:227], v[14:17]
	v_mfma_f32_16x16x32_bf16 v[10:13], v[138:141], v[224:227], v[10:13]
	v_mfma_f32_16x16x32_bf16 v[62:65], v[134:137], v[204:207], v[62:65]
	v_mfma_f32_16x16x32_bf16 v[58:61], v[142:145], v[204:207], v[58:61]
	v_mfma_f32_16x16x32_bf16 v[46:49], v[134:137], v[212:215], v[46:49]
	v_mfma_f32_16x16x32_bf16 v[42:45], v[142:145], v[212:215], v[42:45]
	v_mfma_f32_16x16x32_bf16 v[30:33], v[134:137], v[220:223], v[30:33]
	v_mfma_f32_16x16x32_bf16 v[26:29], v[142:145], v[220:223], v[26:29]
	v_mfma_f32_16x16x32_bf16 v[14:17], v[134:137], v[228:231], v[14:17]
	v_mfma_f32_16x16x32_bf16 v[10:13], v[142:145], v[228:231], v[10:13]
	v_mfma_f32_16x16x32_bf16 v[54:57], v[146:149], v[200:203], v[54:57]
	v_mfma_f32_16x16x32_bf16 v[50:53], v[172:175], v[200:203], v[50:53]
	v_mfma_f32_16x16x32_bf16 v[38:41], v[146:149], v[208:211], v[38:41]
	v_mfma_f32_16x16x32_bf16 v[34:37], v[172:175], v[208:211], v[34:37]
	v_mfma_f32_16x16x32_bf16 v[22:25], v[146:149], v[216:219], v[22:25]
	v_mfma_f32_16x16x32_bf16 v[18:21], v[172:175], v[216:219], v[18:21]
	v_mfma_f32_16x16x32_bf16 v[6:9], v[146:149], v[224:227], v[6:9]
	v_mfma_f32_16x16x32_bf16 v[2:5], v[172:175], v[224:227], v[2:5]
	v_mfma_f32_16x16x32_bf16 v[54:57], v[150:153], v[204:207], v[54:57]
	v_mfma_f32_16x16x32_bf16 v[50:53], v[196:199], v[204:207], v[50:53]
	v_mfma_f32_16x16x32_bf16 v[38:41], v[150:153], v[212:215], v[38:41]
	v_mfma_f32_16x16x32_bf16 v[34:37], v[196:199], v[212:215], v[34:37]
	v_mfma_f32_16x16x32_bf16 v[22:25], v[150:153], v[220:223], v[22:25]
	v_mfma_f32_16x16x32_bf16 v[18:21], v[196:199], v[220:223], v[18:21]
	v_mfma_f32_16x16x32_bf16 v[6:9], v[150:153], v[228:231], v[6:9]
	v_mfma_f32_16x16x32_bf16 v[2:5], v[196:199], v[228:231], v[2:5]
	s_setprio 0
	s_barrier
	s_mov_b32 m0, s46
	s_nop 0
	global_load_lds_dwordx4 v158, s[40:41]
	s_add_i32 s62, 0, 0x18000
	s_add_i32 s63, 0, 0x1c000
	v_add_u32_e32 v142, s62, v182
	v_add_u32_e32 v195, s63, v182
	ds_read_b128 v[130:133], v142
	ds_read_b128 v[134:137], v142 offset:1024
	ds_read_b128 v[138:141], v142 offset:2048
	ds_read_b128 v[142:145], v142 offset:3072
	ds_read_b128 v[146:149], v195
	ds_read_b128 v[150:153], v195 offset:1024
	ds_read_b128 v[172:175], v195 offset:2048
	ds_read_b128 v[196:199], v195 offset:3072
	s_add_u32 s40, s40, 0x40000
	s_addc_u32 s41, s41, 0
	s_mov_b32 m0, s47
	v_lshl_add_u64 v[238:239], s[40:41], 0, v[154:155]
	ds_read_b128 v[200:203], v186 offset:32768
	ds_read_b128 v[204:207], v186 offset:33792
	ds_read_b128 v[208:211], v186 offset:34816
	ds_read_b128 v[212:215], v186 offset:35840
	ds_read_b128 v[216:219], v186 offset:36864
	ds_read_b128 v[220:223], v186 offset:37888
	ds_read_b128 v[224:227], v186 offset:38912
	ds_read_b128 v[228:231], v186 offset:39936
	global_load_lds_dwordx4 v[238:239], off
	v_lshl_add_u64 v[238:239], s[40:41], 0, v[158:159]
	s_mov_b32 m0, s48
	s_nop 0
	global_load_lds_dwordx4 v[238:239], off
	s_waitcnt vmcnt(8)
	s_waitcnt lgkmcnt(0)
	v_mfma_f32_16x16x32_bf16 v[126:129], v[130:133], v[200:203], v[126:129]
	v_mfma_f32_16x16x32_bf16 v[122:125], v[138:141], v[200:203], v[122:125]
	v_mfma_f32_16x16x32_bf16 v[110:113], v[130:133], v[208:211], v[110:113]
	v_mfma_f32_16x16x32_bf16 v[106:109], v[138:141], v[208:211], v[106:109]
	s_barrier
	s_setprio 1
	v_mfma_f32_16x16x32_bf16 v[94:97], v[130:133], v[216:219], v[94:97]
	v_mfma_f32_16x16x32_bf16 v[90:93], v[138:141], v[216:219], v[90:93]
	v_mfma_f32_16x16x32_bf16 v[78:81], v[130:133], v[224:227], v[78:81]
	v_mfma_f32_16x16x32_bf16 v[74:77], v[138:141], v[224:227], v[74:77]
	v_mfma_f32_16x16x32_bf16 v[126:129], v[134:137], v[204:207], v[126:129]
	v_mfma_f32_16x16x32_bf16 v[122:125], v[142:145], v[204:207], v[122:125]
	v_mfma_f32_16x16x32_bf16 v[110:113], v[134:137], v[212:215], v[110:113]
	v_mfma_f32_16x16x32_bf16 v[106:109], v[142:145], v[212:215], v[106:109]
	v_mfma_f32_16x16x32_bf16 v[94:97], v[134:137], v[220:223], v[94:97]
	v_mfma_f32_16x16x32_bf16 v[90:93], v[142:145], v[220:223], v[90:93]
	v_mfma_f32_16x16x32_bf16 v[78:81], v[134:137], v[228:231], v[78:81]
	v_mfma_f32_16x16x32_bf16 v[74:77], v[142:145], v[228:231], v[74:77]
	v_mfma_f32_16x16x32_bf16 v[118:121], v[146:149], v[200:203], v[118:121]
	v_mfma_f32_16x16x32_bf16 v[114:117], v[172:175], v[200:203], v[114:117]
	v_mfma_f32_16x16x32_bf16 v[102:105], v[146:149], v[208:211], v[102:105]
	v_mfma_f32_16x16x32_bf16 v[98:101], v[172:175], v[208:211], v[98:101]
	v_mfma_f32_16x16x32_bf16 v[86:89], v[146:149], v[216:219], v[86:89]
	v_mfma_f32_16x16x32_bf16 v[82:85], v[172:175], v[216:219], v[82:85]
	v_mfma_f32_16x16x32_bf16 v[70:73], v[146:149], v[224:227], v[70:73]
	v_mfma_f32_16x16x32_bf16 v[66:69], v[172:175], v[224:227], v[66:69]
	v_mfma_f32_16x16x32_bf16 v[118:121], v[150:153], v[204:207], v[118:121]
	v_mfma_f32_16x16x32_bf16 v[114:117], v[196:199], v[204:207], v[114:117]
	v_mfma_f32_16x16x32_bf16 v[102:105], v[150:153], v[212:215], v[102:105]
	v_mfma_f32_16x16x32_bf16 v[98:101], v[196:199], v[212:215], v[98:101]
	v_mfma_f32_16x16x32_bf16 v[86:89], v[150:153], v[220:223], v[86:89]
	v_mfma_f32_16x16x32_bf16 v[82:85], v[196:199], v[220:223], v[82:85]
	v_mfma_f32_16x16x32_bf16 v[70:73], v[150:153], v[228:231], v[70:73]
	v_mfma_f32_16x16x32_bf16 v[66:69], v[196:199], v[228:231], v[66:69]
	s_setprio 0
	s_barrier
	s_add_i32 s40, s62, s44
	v_lshl_add_u64 v[176:177], v[176:177], 0, s[18:19]
	s_mov_b32 m0, s40
	ds_read_b128 v[200:203], v186 offset:49152
	ds_read_b128 v[204:207], v186 offset:50176
	ds_read_b128 v[208:211], v186 offset:51200
	ds_read_b128 v[212:215], v186 offset:52224
	ds_read_b128 v[216:219], v186 offset:53248
	ds_read_b128 v[220:223], v186 offset:54272
	ds_read_b128 v[224:227], v186 offset:55296
	ds_read_b128 v[228:231], v186 offset:56320
	global_load_lds_dwordx4 v[176:177], off
	s_add_i32 m0, s40, 0x2000
	s_add_u32 s38, s38, 0x40080
	v_lshl_add_u64 v[176:177], v[232:233], 0, s[18:19]
	s_addc_u32 s39, s39, 0
	s_add_i32 s40, s63, s44
	global_load_lds_dwordx4 v[176:177], off
	v_lshl_add_u64 v[176:177], s[38:39], 0, v[156:157]
	s_mov_b32 m0, s40
	s_nop 0
	global_load_lds_dwordx4 v[176:177], off
	v_lshl_add_u64 v[176:177], s[38:39], 0, v[160:161]
	s_add_i32 m0, s40, 0x2000
	s_nop 0
	global_load_lds_dwordx4 v[176:177], off
	v_lshl_add_u64 v[176:177], v[234:235], 0, s[18:19]
	s_mov_b32 m0, s33
	s_nop 0
	global_load_lds_dwordx4 v[176:177], off
	s_waitcnt vmcnt(7)
	s_waitcnt lgkmcnt(0)
	v_mfma_f32_16x16x32_bf16 v[62:65], v[130:133], v[200:203], v[62:65]
	v_mfma_f32_16x16x32_bf16 v[58:61], v[138:141], v[200:203], v[58:61]
	v_mfma_f32_16x16x32_bf16 v[46:49], v[130:133], v[208:211], v[46:49]
	v_mfma_f32_16x16x32_bf16 v[42:45], v[138:141], v[208:211], v[42:45]
	s_barrier
	s_setprio 1
	v_mfma_f32_16x16x32_bf16 v[30:33], v[130:133], v[216:219], v[30:33]
	v_mfma_f32_16x16x32_bf16 v[26:29], v[138:141], v[216:219], v[26:29]
	v_mfma_f32_16x16x32_bf16 v[14:17], v[130:133], v[224:227], v[14:17]
	v_mfma_f32_16x16x32_bf16 v[10:13], v[138:141], v[224:227], v[10:13]
	v_mfma_f32_16x16x32_bf16 v[62:65], v[134:137], v[204:207], v[62:65]
	v_mfma_f32_16x16x32_bf16 v[58:61], v[142:145], v[204:207], v[58:61]
	v_mfma_f32_16x16x32_bf16 v[46:49], v[134:137], v[212:215], v[46:49]
	v_mfma_f32_16x16x32_bf16 v[42:45], v[142:145], v[212:215], v[42:45]
	v_mfma_f32_16x16x32_bf16 v[30:33], v[134:137], v[220:223], v[30:33]
	v_mfma_f32_16x16x32_bf16 v[26:29], v[142:145], v[220:223], v[26:29]
	v_mfma_f32_16x16x32_bf16 v[14:17], v[134:137], v[228:231], v[14:17]
	v_mfma_f32_16x16x32_bf16 v[10:13], v[142:145], v[228:231], v[10:13]
	v_mfma_f32_16x16x32_bf16 v[54:57], v[146:149], v[200:203], v[54:57]
	v_mfma_f32_16x16x32_bf16 v[50:53], v[172:175], v[200:203], v[50:53]
	v_mfma_f32_16x16x32_bf16 v[38:41], v[146:149], v[208:211], v[38:41]
	v_mfma_f32_16x16x32_bf16 v[34:37], v[172:175], v[208:211], v[34:37]
	v_mfma_f32_16x16x32_bf16 v[22:25], v[146:149], v[216:219], v[22:25]
	v_mfma_f32_16x16x32_bf16 v[18:21], v[172:175], v[216:219], v[18:21]
	v_mfma_f32_16x16x32_bf16 v[6:9], v[146:149], v[224:227], v[6:9]
	v_mfma_f32_16x16x32_bf16 v[2:5], v[172:175], v[224:227], v[2:5]
	v_mfma_f32_16x16x32_bf16 v[54:57], v[150:153], v[204:207], v[54:57]
	v_mfma_f32_16x16x32_bf16 v[50:53], v[196:199], v[204:207], v[50:53]
	v_mfma_f32_16x16x32_bf16 v[38:41], v[150:153], v[212:215], v[38:41]
	v_mfma_f32_16x16x32_bf16 v[34:37], v[196:199], v[212:215], v[34:37]
	v_mfma_f32_16x16x32_bf16 v[22:25], v[150:153], v[220:223], v[22:25]
	v_mfma_f32_16x16x32_bf16 v[18:21], v[196:199], v[220:223], v[18:21]
	v_mfma_f32_16x16x32_bf16 v[6:9], v[150:153], v[228:231], v[6:9]
	v_mfma_f32_16x16x32_bf16 v[2:5], v[196:199], v[228:231], v[2:5]
	s_setprio 0
	s_barrier
	s_add_i32 s61, s61, 2
	s_add_u32 s59, s59, 0x100
	s_addc_u32 s60, s60, 0
	s_add_u32 s36, s36, 0x100
	s_addc_u32 s37, s37, 0
	s_cmp_gt_u32 s61, 13
	s_cbranch_scc0 .LBB0_1308
	s_and_b64 vcc, exec, s[20:21]
	s_cbranch_vccz .LBB0_1311
	s_barrier

.LBB0_1477:
	s_add_u32 s98, s6, 0xfffc0000
	s_addc_u32 s99, s7, -1
	s_mov_b32 m0, s49
	s_nop 0
	global_load_lds_dwordx4 v150, s[98:99]
	ds_read_b128 v[82:85], v180
	ds_read_b128 v[86:89], v180 offset:1024
	ds_read_b128 v[90:93], v180 offset:2048
	ds_read_b128 v[94:97], v180 offset:3072
	ds_read_b128 v[168:171], v181
	ds_read_b128 v[192:195], v181 offset:1024
	ds_read_b128 v[196:199], v181 offset:2048
	ds_read_b128 v[200:203], v181 offset:3072
	s_add_u32 s8, s6, 0xfffc0080
	s_addc_u32 s9, s7, -1
	s_cmp_eq_u32 s61, 12
	s_cselect_b32 s37, s25, s9
	s_cselect_b32 s36, s57, s8
	s_cselect_b32 s9, s23, s60
	s_cselect_b32 s8, s58, s59
	v_lshl_add_u64 v[172:173], s[6:7], 0, v[160:161]
	s_add_i32 m0, s31, 0xc000
	ds_read_b128 v[204:207], v182
	ds_read_b128 v[208:211], v182 offset:1024
	ds_read_b128 v[212:215], v182 offset:2048
	ds_read_b128 v[216:219], v182 offset:3072
	ds_read_b128 v[220:223], v182 offset:4096
	ds_read_b128 v[224:227], v182 offset:5120
	ds_read_b128 v[228:231], v182 offset:6144
	ds_read_b128 v[232:235], v182 offset:7168
	global_load_lds_dwordx4 v[172:173], off
	v_lshl_add_u64 v[172:173], s[6:7], 0, v[158:159]
	s_add_i32 m0, s31, 0xe000
	s_nop 0
	global_load_lds_dwordx4 v[172:173], off
	s_waitcnt vmcnt(8)
	s_waitcnt lgkmcnt(0)
	v_mfma_f32_16x16x32_bf16 v[142:145], v[82:85], v[204:207], v[142:145]
	v_mfma_f32_16x16x32_bf16 v[138:141], v[90:93], v[204:207], v[138:141]
	v_mfma_f32_16x16x32_bf16 v[126:129], v[82:85], v[212:215], v[126:129]
	v_mfma_f32_16x16x32_bf16 v[122:125], v[90:93], v[212:215], v[122:125]
	s_barrier
	s_setprio 1
	v_mfma_f32_16x16x32_bf16 v[110:113], v[82:85], v[220:223], v[110:113]
	v_mfma_f32_16x16x32_bf16 v[106:109], v[90:93], v[220:223], v[106:109]
	v_mfma_f32_16x16x32_bf16 v[78:81], v[82:85], v[228:231], v[78:81]
	v_mfma_f32_16x16x32_bf16 v[74:77], v[90:93], v[228:231], v[74:77]
	v_mfma_f32_16x16x32_bf16 v[142:145], v[86:89], v[208:211], v[142:145]
	v_mfma_f32_16x16x32_bf16 v[138:141], v[94:97], v[208:211], v[138:141]
	v_mfma_f32_16x16x32_bf16 v[126:129], v[86:89], v[216:219], v[126:129]
	v_mfma_f32_16x16x32_bf16 v[122:125], v[94:97], v[216:219], v[122:125]
	v_mfma_f32_16x16x32_bf16 v[110:113], v[86:89], v[224:227], v[110:113]
	v_mfma_f32_16x16x32_bf16 v[106:109], v[94:97], v[224:227], v[106:109]
	v_mfma_f32_16x16x32_bf16 v[78:81], v[86:89], v[232:235], v[78:81]
	v_mfma_f32_16x16x32_bf16 v[74:77], v[94:97], v[232:235], v[74:77]
	v_mfma_f32_16x16x32_bf16 v[134:137], v[168:171], v[204:207], v[134:137]
	v_mfma_f32_16x16x32_bf16 v[130:133], v[196:199], v[204:207], v[130:133]
	v_mfma_f32_16x16x32_bf16 v[118:121], v[168:171], v[212:215], v[118:121]
	v_mfma_f32_16x16x32_bf16 v[114:117], v[196:199], v[212:215], v[114:117]
	v_mfma_f32_16x16x32_bf16 v[102:105], v[168:171], v[220:223], v[102:105]
	v_mfma_f32_16x16x32_bf16 v[98:101], v[196:199], v[220:223], v[98:101]
	v_mfma_f32_16x16x32_bf16 v[70:73], v[168:171], v[228:231], v[70:73]
	v_mfma_f32_16x16x32_bf16 v[66:69], v[196:199], v[228:231], v[66:69]
	v_mfma_f32_16x16x32_bf16 v[134:137], v[192:195], v[208:211], v[134:137]
	v_mfma_f32_16x16x32_bf16 v[130:133], v[200:203], v[208:211], v[130:133]
	v_mfma_f32_16x16x32_bf16 v[118:121], v[192:195], v[216:219], v[118:121]
	v_mfma_f32_16x16x32_bf16 v[114:117], v[200:203], v[216:219], v[114:117]
	v_mfma_f32_16x16x32_bf16 v[102:105], v[192:195], v[224:227], v[102:105]
	v_mfma_f32_16x16x32_bf16 v[98:101], v[200:203], v[224:227], v[98:101]
	v_mfma_f32_16x16x32_bf16 v[70:73], v[192:195], v[232:235], v[70:73]
	v_mfma_f32_16x16x32_bf16 v[66:69], v[200:203], v[232:235], v[66:69]
	s_setprio 0
	s_barrier
	s_add_i32 s62, s54, s41
	v_lshl_add_u64 v[172:173], s[8:9], 0, v[148:149]
	s_mov_b32 m0, s62
	ds_read_b128 v[204:207], v182 offset:16384
	ds_read_b128 v[208:211], v182 offset:17408
	ds_read_b128 v[212:215], v182 offset:18432
	ds_read_b128 v[216:219], v182 offset:19456
	ds_read_b128 v[220:223], v182 offset:20480
	ds_read_b128 v[224:227], v182 offset:21504
	ds_read_b128 v[228:231], v182 offset:22528
	ds_read_b128 v[232:235], v182 offset:23552
	global_load_lds_dwordx4 v[172:173], off
	s_add_i32 m0, s62, 0x2000
	s_add_u32 s62, s8, 0x40000
	v_lshl_add_u64 v[236:237], s[8:9], 0, v[152:153]
	s_addc_u32 s63, s9, 0
	s_add_i32 s64, s55, s41
	global_load_lds_dwordx4 v[236:237], off
	v_lshl_add_u64 v[238:239], s[62:63], 0, v[148:149]
	s_mov_b32 m0, s64
	v_lshl_add_u64 v[240:241], s[36:37], 0, v[150:151]
	global_load_lds_dwordx4 v[238:239], off
	v_lshl_add_u64 v[238:239], s[62:63], 0, v[152:153]
	s_add_i32 m0, s64, 0x2000
	s_nop 0
	global_load_lds_dwordx4 v[238:239], off
	v_lshl_add_u64 v[238:239], s[36:37], 0, v[146:147]
	s_mov_b32 m0, s31
	s_nop 0
	global_load_lds_dwordx4 v[238:239], off
	s_waitcnt vmcnt(7)
	s_waitcnt lgkmcnt(0)
	v_mfma_f32_16x16x32_bf16 v[62:65], v[82:85], v[204:207], v[62:65]
	v_mfma_f32_16x16x32_bf16 v[58:61], v[90:93], v[204:207], v[58:61]
	v_mfma_f32_16x16x32_bf16 v[46:49], v[82:85], v[212:215], v[46:49]
	v_mfma_f32_16x16x32_bf16 v[42:45], v[90:93], v[212:215], v[42:45]
	s_barrier
	s_setprio 1
	v_mfma_f32_16x16x32_bf16 v[30:33], v[82:85], v[220:223], v[30:33]
	v_mfma_f32_16x16x32_bf16 v[26:29], v[90:93], v[220:223], v[26:29]
	v_mfma_f32_16x16x32_bf16 v[14:17], v[82:85], v[228:231], v[14:17]
	v_mfma_f32_16x16x32_bf16 v[10:13], v[90:93], v[228:231], v[10:13]
	v_mfma_f32_16x16x32_bf16 v[62:65], v[86:89], v[208:211], v[62:65]
	v_mfma_f32_16x16x32_bf16 v[58:61], v[94:97], v[208:211], v[58:61]
	v_mfma_f32_16x16x32_bf16 v[46:49], v[86:89], v[216:219], v[46:49]
	v_mfma_f32_16x16x32_bf16 v[42:45], v[94:97], v[216:219], v[42:45]
	v_mfma_f32_16x16x32_bf16 v[30:33], v[86:89], v[224:227], v[30:33]
	v_mfma_f32_16x16x32_bf16 v[26:29], v[94:97], v[224:227], v[26:29]
	v_mfma_f32_16x16x32_bf16 v[14:17], v[86:89], v[232:235], v[14:17]
	v_mfma_f32_16x16x32_bf16 v[10:13], v[94:97], v[232:235], v[10:13]
	v_mfma_f32_16x16x32_bf16 v[54:57], v[168:171], v[204:207], v[54:57]
	v_mfma_f32_16x16x32_bf16 v[50:53], v[196:199], v[204:207], v[50:53]
	v_mfma_f32_16x16x32_bf16 v[38:41], v[168:171], v[212:215], v[38:41]
	v_mfma_f32_16x16x32_bf16 v[34:37], v[196:199], v[212:215], v[34:37]
	v_mfma_f32_16x16x32_bf16 v[22:25], v[168:171], v[220:223], v[22:25]
	v_mfma_f32_16x16x32_bf16 v[18:21], v[196:199], v[220:223], v[18:21]
	v_mfma_f32_16x16x32_bf16 v[6:9], v[168:171], v[228:231], v[6:9]
	v_mfma_f32_16x16x32_bf16 v[2:5], v[196:199], v[228:231], v[2:5]
	v_mfma_f32_16x16x32_bf16 v[54:57], v[192:195], v[208:211], v[54:57]
	v_mfma_f32_16x16x32_bf16 v[50:53], v[200:203], v[208:211], v[50:53]
	v_mfma_f32_16x16x32_bf16 v[38:41], v[192:195], v[216:219], v[38:41]
	v_mfma_f32_16x16x32_bf16 v[34:37], v[200:203], v[216:219], v[34:37]
	v_mfma_f32_16x16x32_bf16 v[22:25], v[192:195], v[224:227], v[22:25]
	v_mfma_f32_16x16x32_bf16 v[18:21], v[200:203], v[224:227], v[18:21]
	v_mfma_f32_16x16x32_bf16 v[6:9], v[192:195], v[232:235], v[6:9]
	v_mfma_f32_16x16x32_bf16 v[2:5], v[200:203], v[232:235], v[2:5]
	s_setprio 0
	s_barrier
	s_mov_b32 m0, s35
	s_nop 0
	global_load_lds_dwordx4 v150, s[36:37]
	s_add_i32 s62, 0, 0x18000
	s_add_i32 s63, 0, 0x1c000
	v_add_u32_e32 v94, s62, v177
	v_add_u32_e32 v166, s63, v177
	ds_read_b128 v[82:85], v94
	ds_read_b128 v[86:89], v94 offset:1024
	ds_read_b128 v[90:93], v94 offset:2048
	ds_read_b128 v[94:97], v94 offset:3072
	ds_read_b128 v[168:171], v166
	ds_read_b128 v[192:195], v166 offset:1024
	ds_read_b128 v[196:199], v166 offset:2048
	ds_read_b128 v[200:203], v166 offset:3072
	s_add_u32 s36, s36, 0x40000
	s_addc_u32 s37, s37, 0
	s_mov_b32 m0, s42
	v_lshl_add_u64 v[242:243], s[36:37], 0, v[146:147]
	ds_read_b128 v[204:207], v182 offset:32768
	ds_read_b128 v[208:211], v182 offset:33792
	ds_read_b128 v[212:215], v182 offset:34816
	ds_read_b128 v[216:219], v182 offset:35840
	ds_read_b128 v[220:223], v182 offset:36864
	ds_read_b128 v[224:227], v182 offset:37888
	ds_read_b128 v[228:231], v182 offset:38912
	ds_read_b128 v[232:235], v182 offset:39936
	global_load_lds_dwordx4 v[242:243], off
	v_lshl_add_u64 v[242:243], s[36:37], 0, v[150:151]
	s_mov_b32 m0, s43
	s_nop 0
	global_load_lds_dwordx4 v[242:243], off
	s_waitcnt vmcnt(8)
	s_waitcnt lgkmcnt(0)
	v_mfma_f32_16x16x32_bf16 v[142:145], v[82:85], v[204:207], v[142:145]
	v_mfma_f32_16x16x32_bf16 v[138:141], v[90:93], v[204:207], v[138:141]
	v_mfma_f32_16x16x32_bf16 v[126:129], v[82:85], v[212:215], v[126:129]
	v_mfma_f32_16x16x32_bf16 v[122:125], v[90:93], v[212:215], v[122:125]
	s_barrier
	s_setprio 1
	v_mfma_f32_16x16x32_bf16 v[110:113], v[82:85], v[220:223], v[110:113]
	v_mfma_f32_16x16x32_bf16 v[106:109], v[90:93], v[220:223], v[106:109]
	v_mfma_f32_16x16x32_bf16 v[78:81], v[82:85], v[228:231], v[78:81]
	v_mfma_f32_16x16x32_bf16 v[74:77], v[90:93], v[228:231], v[74:77]
	v_mfma_f32_16x16x32_bf16 v[142:145], v[86:89], v[208:211], v[142:145]
	v_mfma_f32_16x16x32_bf16 v[138:141], v[94:97], v[208:211], v[138:141]
	v_mfma_f32_16x16x32_bf16 v[126:129], v[86:89], v[216:219], v[126:129]
	v_mfma_f32_16x16x32_bf16 v[122:125], v[94:97], v[216:219], v[122:125]
	v_mfma_f32_16x16x32_bf16 v[110:113], v[86:89], v[224:227], v[110:113]
	v_mfma_f32_16x16x32_bf16 v[106:109], v[94:97], v[224:227], v[106:109]
	v_mfma_f32_16x16x32_bf16 v[78:81], v[86:89], v[232:235], v[78:81]
	v_mfma_f32_16x16x32_bf16 v[74:77], v[94:97], v[232:235], v[74:77]
	v_mfma_f32_16x16x32_bf16 v[134:137], v[168:171], v[204:207], v[134:137]
	v_mfma_f32_16x16x32_bf16 v[130:133], v[196:199], v[204:207], v[130:133]
	v_mfma_f32_16x16x32_bf16 v[118:121], v[168:171], v[212:215], v[118:121]
	v_mfma_f32_16x16x32_bf16 v[114:117], v[196:199], v[212:215], v[114:117]
	v_mfma_f32_16x16x32_bf16 v[102:105], v[168:171], v[220:223], v[102:105]
	v_mfma_f32_16x16x32_bf16 v[98:101], v[196:199], v[220:223], v[98:101]
	v_mfma_f32_16x16x32_bf16 v[70:73], v[168:171], v[228:231], v[70:73]
	v_mfma_f32_16x16x32_bf16 v[66:69], v[196:199], v[228:231], v[66:69]
	v_mfma_f32_16x16x32_bf16 v[134:137], v[192:195], v[208:211], v[134:137]
	v_mfma_f32_16x16x32_bf16 v[130:133], v[200:203], v[208:211], v[130:133]
	v_mfma_f32_16x16x32_bf16 v[118:121], v[192:195], v[216:219], v[118:121]
	v_mfma_f32_16x16x32_bf16 v[114:117], v[200:203], v[216:219], v[114:117]
	v_mfma_f32_16x16x32_bf16 v[102:105], v[192:195], v[224:227], v[102:105]
	v_mfma_f32_16x16x32_bf16 v[98:101], v[200:203], v[224:227], v[98:101]
	v_mfma_f32_16x16x32_bf16 v[70:73], v[192:195], v[232:235], v[70:73]
	v_mfma_f32_16x16x32_bf16 v[66:69], v[200:203], v[232:235], v[66:69]
	s_setprio 0
	s_barrier
	s_add_i32 s36, s62, s41
	v_lshl_add_u64 v[172:173], v[172:173], 0, s[12:13]
	s_mov_b32 m0, s36
	ds_read_b128 v[204:207], v182 offset:49152
	ds_read_b128 v[208:211], v182 offset:50176
	ds_read_b128 v[212:215], v182 offset:51200
	ds_read_b128 v[216:219], v182 offset:52224
	ds_read_b128 v[220:223], v182 offset:53248
	ds_read_b128 v[224:227], v182 offset:54272
	ds_read_b128 v[228:231], v182 offset:55296
	ds_read_b128 v[232:235], v182 offset:56320
	global_load_lds_dwordx4 v[172:173], off
	s_add_i32 m0, s36, 0x2000
	s_add_u32 s8, s8, 0x40080
	v_lshl_add_u64 v[172:173], v[236:237], 0, s[12:13]
	s_addc_u32 s9, s9, 0
	s_add_i32 s36, s63, s41
	global_load_lds_dwordx4 v[172:173], off
	v_lshl_add_u64 v[172:173], s[8:9], 0, v[148:149]
	s_mov_b32 m0, s36
	s_nop 0
	global_load_lds_dwordx4 v[172:173], off
	v_lshl_add_u64 v[172:173], s[8:9], 0, v[152:153]
	s_add_i32 m0, s36, 0x2000
	s_nop 0
	global_load_lds_dwordx4 v[172:173], off
	v_lshl_add_u64 v[172:173], v[238:239], 0, s[12:13]
	s_mov_b32 m0, s48
	s_nop 0
	global_load_lds_dwordx4 v[172:173], off
	s_waitcnt vmcnt(7)
	s_waitcnt lgkmcnt(0)
	v_mfma_f32_16x16x32_bf16 v[62:65], v[82:85], v[204:207], v[62:65]
	v_mfma_f32_16x16x32_bf16 v[58:61], v[90:93], v[204:207], v[58:61]
	v_mfma_f32_16x16x32_bf16 v[46:49], v[82:85], v[212:215], v[46:49]
	v_mfma_f32_16x16x32_bf16 v[42:45], v[90:93], v[212:215], v[42:45]
	s_barrier
	s_setprio 1
	v_mfma_f32_16x16x32_bf16 v[30:33], v[82:85], v[220:223], v[30:33]
	v_mfma_f32_16x16x32_bf16 v[26:29], v[90:93], v[220:223], v[26:29]
	v_mfma_f32_16x16x32_bf16 v[14:17], v[82:85], v[228:231], v[14:17]
	v_mfma_f32_16x16x32_bf16 v[10:13], v[90:93], v[228:231], v[10:13]
	v_mfma_f32_16x16x32_bf16 v[62:65], v[86:89], v[208:211], v[62:65]
	v_mfma_f32_16x16x32_bf16 v[58:61], v[94:97], v[208:211], v[58:61]
	v_mfma_f32_16x16x32_bf16 v[46:49], v[86:89], v[216:219], v[46:49]
	v_mfma_f32_16x16x32_bf16 v[42:45], v[94:97], v[216:219], v[42:45]
	v_mfma_f32_16x16x32_bf16 v[30:33], v[86:89], v[224:227], v[30:33]
	v_mfma_f32_16x16x32_bf16 v[26:29], v[94:97], v[224:227], v[26:29]
	v_mfma_f32_16x16x32_bf16 v[14:17], v[86:89], v[232:235], v[14:17]
	v_mfma_f32_16x16x32_bf16 v[10:13], v[94:97], v[232:235], v[10:13]
	v_mfma_f32_16x16x32_bf16 v[54:57], v[168:171], v[204:207], v[54:57]
	v_mfma_f32_16x16x32_bf16 v[50:53], v[196:199], v[204:207], v[50:53]
	v_mfma_f32_16x16x32_bf16 v[38:41], v[168:171], v[212:215], v[38:41]
	v_mfma_f32_16x16x32_bf16 v[34:37], v[196:199], v[212:215], v[34:37]
	v_mfma_f32_16x16x32_bf16 v[22:25], v[168:171], v[220:223], v[22:25]
	v_mfma_f32_16x16x32_bf16 v[18:21], v[196:199], v[220:223], v[18:21]
	v_mfma_f32_16x16x32_bf16 v[6:9], v[168:171], v[228:231], v[6:9]
	v_mfma_f32_16x16x32_bf16 v[2:5], v[196:199], v[228:231], v[2:5]
	v_mfma_f32_16x16x32_bf16 v[54:57], v[192:195], v[208:211], v[54:57]
	v_mfma_f32_16x16x32_bf16 v[50:53], v[200:203], v[208:211], v[50:53]
	v_mfma_f32_16x16x32_bf16 v[38:41], v[192:195], v[216:219], v[38:41]
	v_mfma_f32_16x16x32_bf16 v[34:37], v[200:203], v[216:219], v[34:37]
	v_mfma_f32_16x16x32_bf16 v[22:25], v[192:195], v[224:227], v[22:25]
	v_mfma_f32_16x16x32_bf16 v[18:21], v[200:203], v[224:227], v[18:21]
	v_mfma_f32_16x16x32_bf16 v[6:9], v[192:195], v[232:235], v[6:9]
	v_mfma_f32_16x16x32_bf16 v[2:5], v[200:203], v[232:235], v[2:5]
	s_setprio 0
	s_barrier
	s_add_i32 s61, s61, 2
	s_add_u32 s59, s59, 0x100
	s_addc_u32 s60, s60, 0
	s_add_u32 s6, s6, 0x100
	s_addc_u32 s7, s7, 0
	s_cmp_gt_u32 s61, 13
	s_cbranch_scc0 .LBB0_1477
	s_andn2_b64 vcc, exec, s[2:3]
	s_cbranch_vccnz .Lrs8h_skip2
	v_lshl_add_u32 v204, s24, 8, v176
	v_ashrrev_i32_e32 v205, 31, v204
	v_lshlrev_b64 v[196:197], 6, v[204:205]
	v_lshl_add_u64 v[212:213], v[156:157], 0, v[196:197]
	v_or_b32_e32 v196, 16, v204
	v_or_b32_e32 v206, 32, v204
	v_or_b32_e32 v204, 48, v204
	v_ashrrev_i32_e32 v197, 31, v196
	v_ashrrev_i32_e32 v207, 31, v206
	v_ashrrev_i32_e32 v205, 31, v204
	v_lshlrev_b64 v[196:197], 6, v[196:197]
	v_lshlrev_b64 v[206:207], 6, v[206:207]
	v_lshlrev_b64 v[204:205], 6, v[204:205]
	v_add_co_u32_e32 v224, vcc, s44, v212
	v_lshl_add_u64 v[200:201], v[156:157], 0, v[196:197]
	v_lshl_add_u64 v[206:207], v[156:157], 0, v[206:207]
	v_lshl_add_u64 v[208:209], v[156:157], 0, v[204:205]
	v_addc_co_u32_e32 v225, vcc, 0, v213, vcc
	flat_load_dwordx4 v[196:199], v[212:213]
	s_nop 0
	flat_load_dwordx4 v[200:203], v[200:201]
	s_nop 0
	flat_load_dwordx4 v[204:207], v[206:207]
	s_nop 0
	flat_load_dwordx4 v[208:211], v[208:209]
	s_nop 0
	flat_load_dwordx4 v[212:215], v[224:225]
	flat_load_dwordx4 v[216:219], v[224:225] offset:1024
	flat_load_dwordx4 v[220:223], v[224:225] offset:2048
	s_nop 0
	flat_load_dwordx4 v[224:227], v[224:225] offset:3072

.LBB0_1817:
	s_add_u32 s98, s42, 0xfffc0000
	s_addc_u32 s99, s43, -1
	s_mov_b32 m0, s60
	s_nop 0
	global_load_lds_dwordx4 v138, s[98:99]
	v_add_u32_e32 v154, s64, v156
	ds_read_b128 v[130:133], v154
	ds_read_b128 v[150:153], v154 offset:1024
	ds_read_b128 v[160:163], v154 offset:2048
	ds_read_b128 v[164:167], v154 offset:3072
	v_add_u32_e32 v154, s65, v156
	ds_read_b128 v[168:171], v154
	ds_read_b128 v[172:175], v154 offset:1024
	ds_read_b128 v[180:183], v154 offset:2048
	ds_read_b128 v[184:187], v154 offset:3072
	s_add_u32 s44, s42, 0xfffc0080
	s_addc_u32 s45, s43, -1
	s_cmp_eq_u32 s70, 12
	s_cselect_b32 s47, s35, s45
	s_cselect_b32 s46, s41, s44
	s_cselect_b32 s45, s31, s69
	s_cselect_b32 s44, s67, s68
	v_lshl_add_u64 v[154:155], s[42:43], 0, v[144:145]
	s_add_i32 m0, s53, 0xc000
	ds_read_b128 v[188:191], v158
	ds_read_b128 v[192:195], v158 offset:1024
	ds_read_b128 v[196:199], v158 offset:2048
	ds_read_b128 v[200:203], v158 offset:3072
	ds_read_b128 v[204:207], v158 offset:4096
	ds_read_b128 v[208:211], v158 offset:5120
	ds_read_b128 v[212:215], v158 offset:6144
	ds_read_b128 v[216:219], v158 offset:7168
	global_load_lds_dwordx4 v[154:155], off
	v_lshl_add_u64 v[154:155], s[42:43], 0, v[142:143]
	s_add_i32 m0, s53, 0xe000
	s_nop 0
	global_load_lds_dwordx4 v[154:155], off
	s_waitcnt vmcnt(8)
	s_waitcnt lgkmcnt(0)
	v_mfma_f32_16x16x32_bf16 v[114:117], v[130:133], v[188:191], v[114:117]
	v_mfma_f32_16x16x32_bf16 v[118:121], v[160:163], v[188:191], v[118:121]
	v_mfma_f32_16x16x32_bf16 v[98:101], v[130:133], v[196:199], v[98:101]
	v_mfma_f32_16x16x32_bf16 v[102:105], v[160:163], v[196:199], v[102:105]
	s_barrier
	s_setprio 1
	v_mfma_f32_16x16x32_bf16 v[82:85], v[130:133], v[204:207], v[82:85]
	v_mfma_f32_16x16x32_bf16 v[86:89], v[160:163], v[204:207], v[86:89]
	v_mfma_f32_16x16x32_bf16 v[66:69], v[130:133], v[212:215], v[66:69]
	v_mfma_f32_16x16x32_bf16 v[70:73], v[160:163], v[212:215], v[70:73]
	v_mfma_f32_16x16x32_bf16 v[114:117], v[150:153], v[192:195], v[114:117]
	v_mfma_f32_16x16x32_bf16 v[118:121], v[164:167], v[192:195], v[118:121]
	v_mfma_f32_16x16x32_bf16 v[98:101], v[150:153], v[200:203], v[98:101]
	v_mfma_f32_16x16x32_bf16 v[102:105], v[164:167], v[200:203], v[102:105]
	v_mfma_f32_16x16x32_bf16 v[82:85], v[150:153], v[208:211], v[82:85]
	v_mfma_f32_16x16x32_bf16 v[86:89], v[164:167], v[208:211], v[86:89]
	v_mfma_f32_16x16x32_bf16 v[66:69], v[150:153], v[216:219], v[66:69]
	v_mfma_f32_16x16x32_bf16 v[70:73], v[164:167], v[216:219], v[70:73]
	v_mfma_f32_16x16x32_bf16 v[122:125], v[168:171], v[188:191], v[122:125]
	v_mfma_f32_16x16x32_bf16 v[126:129], v[180:183], v[188:191], v[126:129]
	v_mfma_f32_16x16x32_bf16 v[106:109], v[168:171], v[196:199], v[106:109]
	v_mfma_f32_16x16x32_bf16 v[110:113], v[180:183], v[196:199], v[110:113]
	v_mfma_f32_16x16x32_bf16 v[90:93], v[168:171], v[204:207], v[90:93]
	v_mfma_f32_16x16x32_bf16 v[94:97], v[180:183], v[204:207], v[94:97]
	v_mfma_f32_16x16x32_bf16 v[74:77], v[168:171], v[212:215], v[74:77]
	v_mfma_f32_16x16x32_bf16 v[78:81], v[180:183], v[212:215], v[78:81]
	v_mfma_f32_16x16x32_bf16 v[122:125], v[172:175], v[192:195], v[122:125]
	v_mfma_f32_16x16x32_bf16 v[126:129], v[184:187], v[192:195], v[126:129]
	v_mfma_f32_16x16x32_bf16 v[106:109], v[172:175], v[200:203], v[106:109]
	v_mfma_f32_16x16x32_bf16 v[110:113], v[184:187], v[200:203], v[110:113]
	v_mfma_f32_16x16x32_bf16 v[90:93], v[172:175], v[208:211], v[90:93]
	v_mfma_f32_16x16x32_bf16 v[94:97], v[184:187], v[208:211], v[94:97]
	v_mfma_f32_16x16x32_bf16 v[74:77], v[172:175], v[216:219], v[74:77]
	v_mfma_f32_16x16x32_bf16 v[78:81], v[184:187], v[216:219], v[78:81]
	s_setprio 0
	s_barrier
	s_add_i32 s71, s64, s52
	v_lshl_add_u64 v[154:155], s[44:45], 0, v[136:137]
	s_mov_b32 m0, s71
	ds_read_b128 v[188:191], v158 offset:16384
	ds_read_b128 v[192:195], v158 offset:17408
	ds_read_b128 v[196:199], v158 offset:18432
	ds_read_b128 v[200:203], v158 offset:19456
	ds_read_b128 v[204:207], v158 offset:20480
	ds_read_b128 v[208:211], v158 offset:21504
	ds_read_b128 v[212:215], v158 offset:22528
	ds_read_b128 v[216:219], v158 offset:23552
	global_load_lds_dwordx4 v[154:155], off
	s_add_i32 m0, s71, 0x2000
	s_add_u32 s72, s44, 0x40000
	v_lshl_add_u64 v[176:177], s[44:45], 0, v[140:141]
	s_addc_u32 s73, s45, 0
	s_add_i32 s71, s65, s52
	global_load_lds_dwordx4 v[176:177], off
	v_lshl_add_u64 v[220:221], s[72:73], 0, v[136:137]
	s_mov_b32 m0, s71
	v_lshl_add_u64 v[222:223], s[46:47], 0, v[138:139]
	global_load_lds_dwordx4 v[220:221], off
	v_lshl_add_u64 v[220:221], s[72:73], 0, v[140:141]
	s_add_i32 m0, s71, 0x2000
	s_nop 0
	global_load_lds_dwordx4 v[220:221], off
	v_lshl_add_u64 v[220:221], s[46:47], 0, v[134:135]
	s_mov_b32 m0, s53
	s_nop 0
	global_load_lds_dwordx4 v[220:221], off
	s_waitcnt vmcnt(7)
	s_waitcnt lgkmcnt(0)
	v_mfma_f32_16x16x32_bf16 v[50:53], v[130:133], v[188:191], v[50:53]
	v_mfma_f32_16x16x32_bf16 v[54:57], v[160:163], v[188:191], v[54:57]
	v_mfma_f32_16x16x32_bf16 v[26:29], v[130:133], v[196:199], v[26:29]
	v_mfma_f32_16x16x32_bf16 v[30:33], v[160:163], v[196:199], v[30:33]
	s_barrier
	s_setprio 1
	v_mfma_f32_16x16x32_bf16 v[18:21], v[130:133], v[204:207], v[18:21]
	v_mfma_f32_16x16x32_bf16 v[22:25], v[160:163], v[204:207], v[22:25]
	v_mfma_f32_16x16x32_bf16 v[2:5], v[130:133], v[212:215], v[2:5]
	v_mfma_f32_16x16x32_bf16 v[6:9], v[160:163], v[212:215], v[6:9]
	v_mfma_f32_16x16x32_bf16 v[50:53], v[150:153], v[192:195], v[50:53]
	v_mfma_f32_16x16x32_bf16 v[54:57], v[164:167], v[192:195], v[54:57]
	v_mfma_f32_16x16x32_bf16 v[26:29], v[150:153], v[200:203], v[26:29]
	v_mfma_f32_16x16x32_bf16 v[30:33], v[164:167], v[200:203], v[30:33]
	v_mfma_f32_16x16x32_bf16 v[18:21], v[150:153], v[208:211], v[18:21]
	v_mfma_f32_16x16x32_bf16 v[22:25], v[164:167], v[208:211], v[22:25]
	v_mfma_f32_16x16x32_bf16 v[2:5], v[150:153], v[216:219], v[2:5]
	v_mfma_f32_16x16x32_bf16 v[6:9], v[164:167], v[216:219], v[6:9]
	v_mfma_f32_16x16x32_bf16 v[58:61], v[168:171], v[188:191], v[58:61]
	v_mfma_f32_16x16x32_bf16 v[62:65], v[180:183], v[188:191], v[62:65]
	v_mfma_f32_16x16x32_bf16 v[42:45], v[168:171], v[196:199], v[42:45]
	v_mfma_f32_16x16x32_bf16 v[46:49], v[180:183], v[196:199], v[46:49]
	v_mfma_f32_16x16x32_bf16 v[34:37], v[168:171], v[204:207], v[34:37]
	v_mfma_f32_16x16x32_bf16 v[38:41], v[180:183], v[204:207], v[38:41]
	v_mfma_f32_16x16x32_bf16 v[10:13], v[168:171], v[212:215], v[10:13]
	v_mfma_f32_16x16x32_bf16 v[14:17], v[180:183], v[212:215], v[14:17]
	v_mfma_f32_16x16x32_bf16 v[58:61], v[172:175], v[192:195], v[58:61]
	v_mfma_f32_16x16x32_bf16 v[62:65], v[184:187], v[192:195], v[62:65]
	v_mfma_f32_16x16x32_bf16 v[42:45], v[172:175], v[200:203], v[42:45]
	v_mfma_f32_16x16x32_bf16 v[46:49], v[184:187], v[200:203], v[46:49]
	v_mfma_f32_16x16x32_bf16 v[34:37], v[172:175], v[208:211], v[34:37]
	v_mfma_f32_16x16x32_bf16 v[38:41], v[184:187], v[208:211], v[38:41]
	v_mfma_f32_16x16x32_bf16 v[10:13], v[172:175], v[216:219], v[10:13]
	v_mfma_f32_16x16x32_bf16 v[14:17], v[184:187], v[216:219], v[14:17]
	s_setprio 0
	s_barrier
	s_mov_b32 m0, s54
	s_nop 0
	global_load_lds_dwordx4 v138, s[46:47]
	s_add_i32 s71, 0, 0x18000
	s_add_i32 s72, 0, 0x1c000
	v_add_u32_e32 v164, s71, v156
	v_add_u32_e32 v179, s72, v156
	ds_read_b128 v[130:133], v164
	ds_read_b128 v[150:153], v164 offset:1024
	ds_read_b128 v[160:163], v164 offset:2048
	ds_read_b128 v[164:167], v164 offset:3072
	ds_read_b128 v[168:171], v179
	ds_read_b128 v[172:175], v179 offset:1024
	ds_read_b128 v[180:183], v179 offset:2048
	ds_read_b128 v[184:187], v179 offset:3072
	s_add_u32 s46, s46, 0x40000
	s_addc_u32 s47, s47, 0
	s_mov_b32 m0, s55
	v_lshl_add_u64 v[224:225], s[46:47], 0, v[134:135]
	ds_read_b128 v[188:191], v158 offset:32768
	ds_read_b128 v[192:195], v158 offset:33792
	ds_read_b128 v[196:199], v158 offset:34816
	ds_read_b128 v[200:203], v158 offset:35840
	ds_read_b128 v[204:207], v158 offset:36864
	ds_read_b128 v[208:211], v158 offset:37888
	ds_read_b128 v[212:215], v158 offset:38912
	ds_read_b128 v[216:219], v158 offset:39936
	global_load_lds_dwordx4 v[224:225], off
	v_lshl_add_u64 v[224:225], s[46:47], 0, v[138:139]
	s_mov_b32 m0, s56
	s_nop 0
	global_load_lds_dwordx4 v[224:225], off
	s_waitcnt vmcnt(8)
	s_waitcnt lgkmcnt(0)
	v_mfma_f32_16x16x32_bf16 v[114:117], v[130:133], v[188:191], v[114:117]
	v_mfma_f32_16x16x32_bf16 v[118:121], v[160:163], v[188:191], v[118:121]
	v_mfma_f32_16x16x32_bf16 v[98:101], v[130:133], v[196:199], v[98:101]
	v_mfma_f32_16x16x32_bf16 v[102:105], v[160:163], v[196:199], v[102:105]
	s_barrier
	s_setprio 1
	v_mfma_f32_16x16x32_bf16 v[82:85], v[130:133], v[204:207], v[82:85]
	v_mfma_f32_16x16x32_bf16 v[86:89], v[160:163], v[204:207], v[86:89]
	v_mfma_f32_16x16x32_bf16 v[66:69], v[130:133], v[212:215], v[66:69]
	v_mfma_f32_16x16x32_bf16 v[70:73], v[160:163], v[212:215], v[70:73]
	v_mfma_f32_16x16x32_bf16 v[114:117], v[150:153], v[192:195], v[114:117]
	v_mfma_f32_16x16x32_bf16 v[118:121], v[164:167], v[192:195], v[118:121]
	v_mfma_f32_16x16x32_bf16 v[98:101], v[150:153], v[200:203], v[98:101]
	v_mfma_f32_16x16x32_bf16 v[102:105], v[164:167], v[200:203], v[102:105]
	v_mfma_f32_16x16x32_bf16 v[82:85], v[150:153], v[208:211], v[82:85]
	v_mfma_f32_16x16x32_bf16 v[86:89], v[164:167], v[208:211], v[86:89]
	v_mfma_f32_16x16x32_bf16 v[66:69], v[150:153], v[216:219], v[66:69]
	v_mfma_f32_16x16x32_bf16 v[70:73], v[164:167], v[216:219], v[70:73]
	v_mfma_f32_16x16x32_bf16 v[122:125], v[168:171], v[188:191], v[122:125]
	v_mfma_f32_16x16x32_bf16 v[126:129], v[180:183], v[188:191], v[126:129]
	v_mfma_f32_16x16x32_bf16 v[106:109], v[168:171], v[196:199], v[106:109]
	v_mfma_f32_16x16x32_bf16 v[110:113], v[180:183], v[196:199], v[110:113]
	v_mfma_f32_16x16x32_bf16 v[90:93], v[168:171], v[204:207], v[90:93]
	v_mfma_f32_16x16x32_bf16 v[94:97], v[180:183], v[204:207], v[94:97]
	v_mfma_f32_16x16x32_bf16 v[74:77], v[168:171], v[212:215], v[74:77]
	v_mfma_f32_16x16x32_bf16 v[78:81], v[180:183], v[212:215], v[78:81]
	v_mfma_f32_16x16x32_bf16 v[122:125], v[172:175], v[192:195], v[122:125]
	v_mfma_f32_16x16x32_bf16 v[126:129], v[184:187], v[192:195], v[126:129]
	v_mfma_f32_16x16x32_bf16 v[106:109], v[172:175], v[200:203], v[106:109]
	v_mfma_f32_16x16x32_bf16 v[110:113], v[184:187], v[200:203], v[110:113]
	v_mfma_f32_16x16x32_bf16 v[90:93], v[172:175], v[208:211], v[90:93]
	v_mfma_f32_16x16x32_bf16 v[94:97], v[184:187], v[208:211], v[94:97]
	v_mfma_f32_16x16x32_bf16 v[74:77], v[172:175], v[216:219], v[74:77]
	v_mfma_f32_16x16x32_bf16 v[78:81], v[184:187], v[216:219], v[78:81]
	s_setprio 0
	s_barrier
	s_add_i32 s46, s71, s52
	v_lshl_add_u64 v[154:155], v[154:155], 0, s[24:25]
	s_mov_b32 m0, s46
	ds_read_b128 v[188:191], v158 offset:49152
	ds_read_b128 v[192:195], v158 offset:50176
	ds_read_b128 v[196:199], v158 offset:51200
	ds_read_b128 v[200:203], v158 offset:52224
	ds_read_b128 v[204:207], v158 offset:53248
	ds_read_b128 v[208:211], v158 offset:54272
	ds_read_b128 v[212:215], v158 offset:55296
	ds_read_b128 v[216:219], v158 offset:56320
	global_load_lds_dwordx4 v[154:155], off
	s_add_i32 m0, s46, 0x2000
	s_add_u32 s44, s44, 0x40080
	v_lshl_add_u64 v[154:155], v[176:177], 0, s[24:25]
	s_addc_u32 s45, s45, 0
	s_add_i32 s46, s72, s52
	global_load_lds_dwordx4 v[154:155], off
	v_lshl_add_u64 v[154:155], s[44:45], 0, v[136:137]
	s_mov_b32 m0, s46
	s_nop 0
	global_load_lds_dwordx4 v[154:155], off
	v_lshl_add_u64 v[154:155], s[44:45], 0, v[140:141]
	s_add_i32 m0, s46, 0x2000
	s_nop 0
	global_load_lds_dwordx4 v[154:155], off
	v_lshl_add_u64 v[154:155], v[220:221], 0, s[24:25]
	s_mov_b32 m0, s59
	s_nop 0
	global_load_lds_dwordx4 v[154:155], off
	s_waitcnt vmcnt(7)
	s_waitcnt lgkmcnt(0)
	v_mfma_f32_16x16x32_bf16 v[50:53], v[130:133], v[188:191], v[50:53]
	v_mfma_f32_16x16x32_bf16 v[54:57], v[160:163], v[188:191], v[54:57]
	v_mfma_f32_16x16x32_bf16 v[26:29], v[130:133], v[196:199], v[26:29]
	v_mfma_f32_16x16x32_bf16 v[30:33], v[160:163], v[196:199], v[30:33]
	s_barrier
	s_setprio 1
	v_mfma_f32_16x16x32_bf16 v[18:21], v[130:133], v[204:207], v[18:21]
	v_mfma_f32_16x16x32_bf16 v[22:25], v[160:163], v[204:207], v[22:25]
	v_mfma_f32_16x16x32_bf16 v[2:5], v[130:133], v[212:215], v[2:5]
	v_mfma_f32_16x16x32_bf16 v[6:9], v[160:163], v[212:215], v[6:9]
	v_mfma_f32_16x16x32_bf16 v[50:53], v[150:153], v[192:195], v[50:53]
	v_mfma_f32_16x16x32_bf16 v[54:57], v[164:167], v[192:195], v[54:57]
	v_mfma_f32_16x16x32_bf16 v[26:29], v[150:153], v[200:203], v[26:29]
	v_mfma_f32_16x16x32_bf16 v[30:33], v[164:167], v[200:203], v[30:33]
	v_mfma_f32_16x16x32_bf16 v[18:21], v[150:153], v[208:211], v[18:21]
	v_mfma_f32_16x16x32_bf16 v[22:25], v[164:167], v[208:211], v[22:25]
	v_mfma_f32_16x16x32_bf16 v[2:5], v[150:153], v[216:219], v[2:5]
	v_mfma_f32_16x16x32_bf16 v[6:9], v[164:167], v[216:219], v[6:9]
	v_mfma_f32_16x16x32_bf16 v[58:61], v[168:171], v[188:191], v[58:61]
	v_mfma_f32_16x16x32_bf16 v[62:65], v[180:183], v[188:191], v[62:65]
	v_mfma_f32_16x16x32_bf16 v[42:45], v[168:171], v[196:199], v[42:45]
	v_mfma_f32_16x16x32_bf16 v[46:49], v[180:183], v[196:199], v[46:49]
	v_mfma_f32_16x16x32_bf16 v[34:37], v[168:171], v[204:207], v[34:37]
	v_mfma_f32_16x16x32_bf16 v[38:41], v[180:183], v[204:207], v[38:41]
	v_mfma_f32_16x16x32_bf16 v[10:13], v[168:171], v[212:215], v[10:13]
	v_mfma_f32_16x16x32_bf16 v[14:17], v[180:183], v[212:215], v[14:17]
	v_mfma_f32_16x16x32_bf16 v[58:61], v[172:175], v[192:195], v[58:61]
	v_mfma_f32_16x16x32_bf16 v[62:65], v[184:187], v[192:195], v[62:65]
	v_mfma_f32_16x16x32_bf16 v[42:45], v[172:175], v[200:203], v[42:45]
	v_mfma_f32_16x16x32_bf16 v[46:49], v[184:187], v[200:203], v[46:49]
	v_mfma_f32_16x16x32_bf16 v[34:37], v[172:175], v[208:211], v[34:37]
	v_mfma_f32_16x16x32_bf16 v[38:41], v[184:187], v[208:211], v[38:41]
	v_mfma_f32_16x16x32_bf16 v[10:13], v[172:175], v[216:219], v[10:13]
	v_mfma_f32_16x16x32_bf16 v[14:17], v[184:187], v[216:219], v[14:17]
	s_setprio 0
	s_barrier
	s_add_i32 s70, s70, 2
	s_add_u32 s68, s68, 0x100
	s_addc_u32 s69, s69, 0
	s_add_u32 s42, s42, 0x100
	s_addc_u32 s43, s43, 0
	s_cmp_gt_u32 s70, 13
	s_cbranch_scc0 .LBB0_1817
	s_and_b64 vcc, exec, s[26:27]
	s_cbranch_vccz .LBB0_1820
	s_barrier

.LBB0_2442:
	s_add_u32 s98, s30, 0xfffc0000
	s_addc_u32 s99, s31, -1
	s_mov_b32 m0, s47
	s_nop 0
	global_load_lds_dwordx4 v148, s[98:99]
	ds_read_b128 v[130:133], v178
	ds_read_b128 v[134:137], v178 offset:1024
	ds_read_b128 v[138:141], v178 offset:2048
	ds_read_b128 v[162:165], v178 offset:3072
	ds_read_b128 v[166:169], v179
	ds_read_b128 v[188:191], v179 offset:1024
	ds_read_b128 v[192:195], v179 offset:2048
	ds_read_b128 v[196:199], v179 offset:3072
	s_add_u32 s34, s30, 0xfffc0080
	s_addc_u32 s35, s31, -1
	s_cmp_eq_u32 s59, 12
	s_cselect_b32 s37, s23, s35
	s_cselect_b32 s36, s55, s34
	s_cselect_b32 s35, s21, s58
	s_cselect_b32 s34, s56, s57
	v_lshl_add_u64 v[142:143], s[30:31], 0, v[156:157]
	s_add_i32 m0, s29, 0xc000
	ds_read_b128 v[200:203], v180
	ds_read_b128 v[204:207], v180 offset:1024
	ds_read_b128 v[208:211], v180 offset:2048
	ds_read_b128 v[212:215], v180 offset:3072
	ds_read_b128 v[216:219], v180 offset:4096
	ds_read_b128 v[220:223], v180 offset:5120
	ds_read_b128 v[224:227], v180 offset:6144
	ds_read_b128 v[228:231], v180 offset:7168
	global_load_lds_dwordx4 v[142:143], off
	v_lshl_add_u64 v[142:143], s[30:31], 0, v[154:155]
	s_add_i32 m0, s29, 0xe000
	s_nop 0
	global_load_lds_dwordx4 v[142:143], off
	s_waitcnt vmcnt(8)
	s_waitcnt lgkmcnt(0)
	v_mfma_f32_16x16x32_bf16 v[124:127], v[130:133], v[200:203], v[124:127]
	v_mfma_f32_16x16x32_bf16 v[120:123], v[138:141], v[200:203], v[120:123]
	v_mfma_f32_16x16x32_bf16 v[108:111], v[130:133], v[208:211], v[108:111]
	v_mfma_f32_16x16x32_bf16 v[104:107], v[138:141], v[208:211], v[104:107]
	s_barrier
	s_setprio 1
	v_mfma_f32_16x16x32_bf16 v[92:95], v[130:133], v[216:219], v[92:95]
	v_mfma_f32_16x16x32_bf16 v[88:91], v[138:141], v[216:219], v[88:91]
	v_mfma_f32_16x16x32_bf16 v[76:79], v[130:133], v[224:227], v[76:79]
	v_mfma_f32_16x16x32_bf16 v[72:75], v[138:141], v[224:227], v[72:75]
	v_mfma_f32_16x16x32_bf16 v[124:127], v[134:137], v[204:207], v[124:127]
	v_mfma_f32_16x16x32_bf16 v[120:123], v[162:165], v[204:207], v[120:123]
	v_mfma_f32_16x16x32_bf16 v[108:111], v[134:137], v[212:215], v[108:111]
	v_mfma_f32_16x16x32_bf16 v[104:107], v[162:165], v[212:215], v[104:107]
	v_mfma_f32_16x16x32_bf16 v[92:95], v[134:137], v[220:223], v[92:95]
	v_mfma_f32_16x16x32_bf16 v[88:91], v[162:165], v[220:223], v[88:91]
	v_mfma_f32_16x16x32_bf16 v[76:79], v[134:137], v[228:231], v[76:79]
	v_mfma_f32_16x16x32_bf16 v[72:75], v[162:165], v[228:231], v[72:75]
	v_mfma_f32_16x16x32_bf16 v[116:119], v[166:169], v[200:203], v[116:119]
	v_mfma_f32_16x16x32_bf16 v[112:115], v[192:195], v[200:203], v[112:115]
	v_mfma_f32_16x16x32_bf16 v[100:103], v[166:169], v[208:211], v[100:103]
	v_mfma_f32_16x16x32_bf16 v[96:99], v[192:195], v[208:211], v[96:99]
	v_mfma_f32_16x16x32_bf16 v[84:87], v[166:169], v[216:219], v[84:87]
	v_mfma_f32_16x16x32_bf16 v[80:83], v[192:195], v[216:219], v[80:83]
	v_mfma_f32_16x16x32_bf16 v[68:71], v[166:169], v[224:227], v[68:71]
	v_mfma_f32_16x16x32_bf16 v[64:67], v[192:195], v[224:227], v[64:67]
	v_mfma_f32_16x16x32_bf16 v[116:119], v[188:191], v[204:207], v[116:119]
	v_mfma_f32_16x16x32_bf16 v[112:115], v[196:199], v[204:207], v[112:115]
	v_mfma_f32_16x16x32_bf16 v[100:103], v[188:191], v[212:215], v[100:103]
	v_mfma_f32_16x16x32_bf16 v[96:99], v[196:199], v[212:215], v[96:99]
	v_mfma_f32_16x16x32_bf16 v[84:87], v[188:191], v[220:223], v[84:87]
	v_mfma_f32_16x16x32_bf16 v[80:83], v[196:199], v[220:223], v[80:83]
	v_mfma_f32_16x16x32_bf16 v[68:71], v[188:191], v[228:231], v[68:71]
	v_mfma_f32_16x16x32_bf16 v[64:67], v[196:199], v[228:231], v[64:67]
	s_setprio 0
	s_barrier
	s_add_i32 s60, s49, s40
	v_lshl_add_u64 v[142:143], s[34:35], 0, v[146:147]
	s_mov_b32 m0, s60
	ds_read_b128 v[200:203], v180 offset:16384
	ds_read_b128 v[204:207], v180 offset:17408
	ds_read_b128 v[208:211], v180 offset:18432
	ds_read_b128 v[212:215], v180 offset:19456
	ds_read_b128 v[216:219], v180 offset:20480
	ds_read_b128 v[220:223], v180 offset:21504
	ds_read_b128 v[224:227], v180 offset:22528
	ds_read_b128 v[228:231], v180 offset:23552
	global_load_lds_dwordx4 v[142:143], off
	s_add_i32 m0, s60, 0x2000
	s_add_u32 s60, s34, 0x40000
	v_lshl_add_u64 v[170:171], s[34:35], 0, v[150:151]
	s_addc_u32 s61, s35, 0
	s_add_i32 s62, s50, s40
	global_load_lds_dwordx4 v[170:171], off
	v_lshl_add_u64 v[232:233], s[60:61], 0, v[146:147]
	s_mov_b32 m0, s62
	v_lshl_add_u64 v[234:235], s[36:37], 0, v[148:149]
	global_load_lds_dwordx4 v[232:233], off
	v_lshl_add_u64 v[232:233], s[60:61], 0, v[150:151]
	s_add_i32 m0, s62, 0x2000
	s_nop 0
	global_load_lds_dwordx4 v[232:233], off
	v_lshl_add_u64 v[232:233], s[36:37], 0, v[144:145]
	s_mov_b32 m0, s29
	s_nop 0
	global_load_lds_dwordx4 v[232:233], off
	s_waitcnt vmcnt(7)
	s_waitcnt lgkmcnt(0)
	v_mfma_f32_16x16x32_bf16 v[60:63], v[130:133], v[200:203], v[60:63]
	v_mfma_f32_16x16x32_bf16 v[56:59], v[138:141], v[200:203], v[56:59]
	v_mfma_f32_16x16x32_bf16 v[44:47], v[130:133], v[208:211], v[44:47]
	v_mfma_f32_16x16x32_bf16 v[40:43], v[138:141], v[208:211], v[40:43]
	s_barrier
	s_setprio 1
	v_mfma_f32_16x16x32_bf16 v[28:31], v[130:133], v[216:219], v[28:31]
	v_mfma_f32_16x16x32_bf16 v[24:27], v[138:141], v[216:219], v[24:27]
	v_mfma_f32_16x16x32_bf16 v[12:15], v[130:133], v[224:227], v[12:15]
	v_mfma_f32_16x16x32_bf16 v[8:11], v[138:141], v[224:227], v[8:11]
	v_mfma_f32_16x16x32_bf16 v[60:63], v[134:137], v[204:207], v[60:63]
	v_mfma_f32_16x16x32_bf16 v[56:59], v[162:165], v[204:207], v[56:59]
	v_mfma_f32_16x16x32_bf16 v[44:47], v[134:137], v[212:215], v[44:47]
	v_mfma_f32_16x16x32_bf16 v[40:43], v[162:165], v[212:215], v[40:43]
	v_mfma_f32_16x16x32_bf16 v[28:31], v[134:137], v[220:223], v[28:31]
	v_mfma_f32_16x16x32_bf16 v[24:27], v[162:165], v[220:223], v[24:27]
	v_mfma_f32_16x16x32_bf16 v[12:15], v[134:137], v[228:231], v[12:15]
	v_mfma_f32_16x16x32_bf16 v[8:11], v[162:165], v[228:231], v[8:11]
	v_mfma_f32_16x16x32_bf16 v[52:55], v[166:169], v[200:203], v[52:55]
	v_mfma_f32_16x16x32_bf16 v[48:51], v[192:195], v[200:203], v[48:51]
	v_mfma_f32_16x16x32_bf16 v[36:39], v[166:169], v[208:211], v[36:39]
	v_mfma_f32_16x16x32_bf16 v[32:35], v[192:195], v[208:211], v[32:35]
	v_mfma_f32_16x16x32_bf16 v[20:23], v[166:169], v[216:219], v[20:23]
	v_mfma_f32_16x16x32_bf16 v[16:19], v[192:195], v[216:219], v[16:19]
	v_mfma_f32_16x16x32_bf16 v[4:7], v[166:169], v[224:227], v[4:7]
	v_mfma_f32_16x16x32_bf16 v[0:3], v[192:195], v[224:227], v[0:3]
	v_mfma_f32_16x16x32_bf16 v[52:55], v[188:191], v[204:207], v[52:55]
	v_mfma_f32_16x16x32_bf16 v[48:51], v[196:199], v[204:207], v[48:51]
	v_mfma_f32_16x16x32_bf16 v[36:39], v[188:191], v[212:215], v[36:39]
	v_mfma_f32_16x16x32_bf16 v[32:35], v[196:199], v[212:215], v[32:35]
	v_mfma_f32_16x16x32_bf16 v[20:23], v[188:191], v[220:223], v[20:23]
	v_mfma_f32_16x16x32_bf16 v[16:19], v[196:199], v[220:223], v[16:19]
	v_mfma_f32_16x16x32_bf16 v[4:7], v[188:191], v[228:231], v[4:7]
	v_mfma_f32_16x16x32_bf16 v[0:3], v[196:199], v[228:231], v[0:3]
	s_setprio 0
	s_barrier
	s_mov_b32 m0, s41
	s_nop 0
	global_load_lds_dwordx4 v148, s[36:37]
	s_add_i32 s60, 0, 0x18000
	v_add_u32_e32 v129, s60, v176
	s_add_i32 s61, 0, 0x1c000
	ds_read_b128 v[130:133], v129
	ds_read_b128 v[134:137], v129 offset:1024
	ds_read_b128 v[138:141], v129 offset:2048
	ds_read_b128 v[162:165], v129 offset:3072
	v_add_u32_e32 v129, s61, v176
	ds_read_b128 v[166:169], v129
	ds_read_b128 v[188:191], v129 offset:1024
	ds_read_b128 v[192:195], v129 offset:2048
	ds_read_b128 v[196:199], v129 offset:3072
	s_add_u32 s36, s36, 0x40000
	s_addc_u32 s37, s37, 0
	s_mov_b32 m0, s42
	v_lshl_add_u64 v[236:237], s[36:37], 0, v[144:145]
	ds_read_b128 v[200:203], v180 offset:32768
	ds_read_b128 v[204:207], v180 offset:33792
	ds_read_b128 v[208:211], v180 offset:34816
	ds_read_b128 v[212:215], v180 offset:35840
	ds_read_b128 v[216:219], v180 offset:36864
	ds_read_b128 v[220:223], v180 offset:37888
	ds_read_b128 v[224:227], v180 offset:38912
	ds_read_b128 v[228:231], v180 offset:39936
	global_load_lds_dwordx4 v[236:237], off
	v_lshl_add_u64 v[236:237], s[36:37], 0, v[148:149]
	s_mov_b32 m0, s43
	s_nop 0
	global_load_lds_dwordx4 v[236:237], off
	s_waitcnt vmcnt(8)
	s_waitcnt lgkmcnt(0)
	v_mfma_f32_16x16x32_bf16 v[124:127], v[130:133], v[200:203], v[124:127]
	v_mfma_f32_16x16x32_bf16 v[120:123], v[138:141], v[200:203], v[120:123]
	v_mfma_f32_16x16x32_bf16 v[108:111], v[130:133], v[208:211], v[108:111]
	v_mfma_f32_16x16x32_bf16 v[104:107], v[138:141], v[208:211], v[104:107]
	s_barrier
	s_setprio 1
	v_mfma_f32_16x16x32_bf16 v[92:95], v[130:133], v[216:219], v[92:95]
	v_mfma_f32_16x16x32_bf16 v[88:91], v[138:141], v[216:219], v[88:91]
	v_mfma_f32_16x16x32_bf16 v[76:79], v[130:133], v[224:227], v[76:79]
	v_mfma_f32_16x16x32_bf16 v[72:75], v[138:141], v[224:227], v[72:75]
	v_mfma_f32_16x16x32_bf16 v[124:127], v[134:137], v[204:207], v[124:127]
	v_mfma_f32_16x16x32_bf16 v[120:123], v[162:165], v[204:207], v[120:123]
	v_mfma_f32_16x16x32_bf16 v[108:111], v[134:137], v[212:215], v[108:111]
	v_mfma_f32_16x16x32_bf16 v[104:107], v[162:165], v[212:215], v[104:107]
	v_mfma_f32_16x16x32_bf16 v[92:95], v[134:137], v[220:223], v[92:95]
	v_mfma_f32_16x16x32_bf16 v[88:91], v[162:165], v[220:223], v[88:91]
	v_mfma_f32_16x16x32_bf16 v[76:79], v[134:137], v[228:231], v[76:79]
	v_mfma_f32_16x16x32_bf16 v[72:75], v[162:165], v[228:231], v[72:75]
	v_mfma_f32_16x16x32_bf16 v[116:119], v[166:169], v[200:203], v[116:119]
	v_mfma_f32_16x16x32_bf16 v[112:115], v[192:195], v[200:203], v[112:115]
	v_mfma_f32_16x16x32_bf16 v[100:103], v[166:169], v[208:211], v[100:103]
	v_mfma_f32_16x16x32_bf16 v[96:99], v[192:195], v[208:211], v[96:99]
	v_mfma_f32_16x16x32_bf16 v[84:87], v[166:169], v[216:219], v[84:87]
	v_mfma_f32_16x16x32_bf16 v[80:83], v[192:195], v[216:219], v[80:83]
	v_mfma_f32_16x16x32_bf16 v[68:71], v[166:169], v[224:227], v[68:71]
	v_mfma_f32_16x16x32_bf16 v[64:67], v[192:195], v[224:227], v[64:67]
	v_mfma_f32_16x16x32_bf16 v[116:119], v[188:191], v[204:207], v[116:119]
	v_mfma_f32_16x16x32_bf16 v[112:115], v[196:199], v[204:207], v[112:115]
	v_mfma_f32_16x16x32_bf16 v[100:103], v[188:191], v[212:215], v[100:103]
	v_mfma_f32_16x16x32_bf16 v[96:99], v[196:199], v[212:215], v[96:99]
	v_mfma_f32_16x16x32_bf16 v[84:87], v[188:191], v[220:223], v[84:87]
	v_mfma_f32_16x16x32_bf16 v[80:83], v[196:199], v[220:223], v[80:83]
	v_mfma_f32_16x16x32_bf16 v[68:71], v[188:191], v[228:231], v[68:71]
	v_mfma_f32_16x16x32_bf16 v[64:67], v[196:199], v[228:231], v[64:67]
	s_setprio 0
	s_barrier
	s_add_i32 s36, s60, s40
	v_lshl_add_u64 v[142:143], v[142:143], 0, s[8:9]
	s_mov_b32 m0, s36
	ds_read_b128 v[200:203], v180 offset:49152
	ds_read_b128 v[204:207], v180 offset:50176
	ds_read_b128 v[208:211], v180 offset:51200
	ds_read_b128 v[212:215], v180 offset:52224
	ds_read_b128 v[216:219], v180 offset:53248
	ds_read_b128 v[220:223], v180 offset:54272
	ds_read_b128 v[224:227], v180 offset:55296
	ds_read_b128 v[228:231], v180 offset:56320
	global_load_lds_dwordx4 v[142:143], off
	s_add_i32 m0, s36, 0x2000
	s_add_u32 s34, s34, 0x40080
	v_lshl_add_u64 v[142:143], v[170:171], 0, s[8:9]
	s_addc_u32 s35, s35, 0
	s_add_i32 s36, s61, s40
	global_load_lds_dwordx4 v[142:143], off
	v_lshl_add_u64 v[142:143], s[34:35], 0, v[146:147]
	s_mov_b32 m0, s36
	s_nop 0
	global_load_lds_dwordx4 v[142:143], off
	v_lshl_add_u64 v[142:143], s[34:35], 0, v[150:151]
	s_add_i32 m0, s36, 0x2000
	s_nop 0
	global_load_lds_dwordx4 v[142:143], off
	v_lshl_add_u64 v[142:143], v[232:233], 0, s[8:9]
	s_mov_b32 m0, s46
	s_nop 0
	global_load_lds_dwordx4 v[142:143], off
	s_waitcnt vmcnt(7)
	s_waitcnt lgkmcnt(0)
	v_mfma_f32_16x16x32_bf16 v[60:63], v[130:133], v[200:203], v[60:63]
	v_mfma_f32_16x16x32_bf16 v[56:59], v[138:141], v[200:203], v[56:59]
	v_mfma_f32_16x16x32_bf16 v[44:47], v[130:133], v[208:211], v[44:47]
	v_mfma_f32_16x16x32_bf16 v[40:43], v[138:141], v[208:211], v[40:43]
	s_barrier
	s_setprio 1
	v_mfma_f32_16x16x32_bf16 v[28:31], v[130:133], v[216:219], v[28:31]
	v_mfma_f32_16x16x32_bf16 v[24:27], v[138:141], v[216:219], v[24:27]
	v_mfma_f32_16x16x32_bf16 v[12:15], v[130:133], v[224:227], v[12:15]
	v_mfma_f32_16x16x32_bf16 v[8:11], v[138:141], v[224:227], v[8:11]
	v_mfma_f32_16x16x32_bf16 v[60:63], v[134:137], v[204:207], v[60:63]
	v_mfma_f32_16x16x32_bf16 v[56:59], v[162:165], v[204:207], v[56:59]
	v_mfma_f32_16x16x32_bf16 v[44:47], v[134:137], v[212:215], v[44:47]
	v_mfma_f32_16x16x32_bf16 v[40:43], v[162:165], v[212:215], v[40:43]
	v_mfma_f32_16x16x32_bf16 v[28:31], v[134:137], v[220:223], v[28:31]
	v_mfma_f32_16x16x32_bf16 v[24:27], v[162:165], v[220:223], v[24:27]
	v_mfma_f32_16x16x32_bf16 v[12:15], v[134:137], v[228:231], v[12:15]
	v_mfma_f32_16x16x32_bf16 v[8:11], v[162:165], v[228:231], v[8:11]
	v_mfma_f32_16x16x32_bf16 v[52:55], v[166:169], v[200:203], v[52:55]
	v_mfma_f32_16x16x32_bf16 v[48:51], v[192:195], v[200:203], v[48:51]
	v_mfma_f32_16x16x32_bf16 v[36:39], v[166:169], v[208:211], v[36:39]
	v_mfma_f32_16x16x32_bf16 v[32:35], v[192:195], v[208:211], v[32:35]
	v_mfma_f32_16x16x32_bf16 v[20:23], v[166:169], v[216:219], v[20:23]
	v_mfma_f32_16x16x32_bf16 v[16:19], v[192:195], v[216:219], v[16:19]
	v_mfma_f32_16x16x32_bf16 v[4:7], v[166:169], v[224:227], v[4:7]
	v_mfma_f32_16x16x32_bf16 v[0:3], v[192:195], v[224:227], v[0:3]
	v_mfma_f32_16x16x32_bf16 v[52:55], v[188:191], v[204:207], v[52:55]
	v_mfma_f32_16x16x32_bf16 v[48:51], v[196:199], v[204:207], v[48:51]
	v_mfma_f32_16x16x32_bf16 v[36:39], v[188:191], v[212:215], v[36:39]
	v_mfma_f32_16x16x32_bf16 v[32:35], v[196:199], v[212:215], v[32:35]
	v_mfma_f32_16x16x32_bf16 v[20:23], v[188:191], v[220:223], v[20:23]
	v_mfma_f32_16x16x32_bf16 v[16:19], v[196:199], v[220:223], v[16:19]
	v_mfma_f32_16x16x32_bf16 v[4:7], v[188:191], v[228:231], v[4:7]
	v_mfma_f32_16x16x32_bf16 v[0:3], v[196:199], v[228:231], v[0:3]
	s_setprio 0
	s_barrier
	s_add_i32 s59, s59, 2
	s_add_u32 s57, s57, 0x100
	s_addc_u32 s58, s58, 0
	s_add_u32 s30, s30, 0x100
	s_addc_u32 s31, s31, 0
	s_cmp_gt_u32 s59, 13
	s_cbranch_scc0 .LBB0_2442
	s_and_b64 vcc, exec, s[10:11]
	s_cbranch_vccz .LBB0_2445
	s_barrier
